# speedup vs baseline: 1.0317x; 1.0054x over previous
;   #define STAGEA(P,br,kt) STAGE(P,A,lda,br,kt,oa0,oa1)
;   #define LDA(dst,b,h) _Pragma("unroll") for(int m=0;m<4;++m) _Pragma("unroll") for(int k=0;k<2;++k) \
;     dst[m][k]=*reinterpret_cast<const bf16x8*>((char*)SA(b,h)+lds_byte(wr*64+m*16+fr,k*32+fq*8))
;   #define LDB(dst,b,h) _Pragma("unroll") for(int n=0;n<2;++n) _Pragma("unroll") for(int k=0;k<2;++k) \
;     dst[n][k]=*reinterpret_cast<const bf16x8*>((char*)SB(b,h)+lds_byte(wc*32+n*16+fr,k*32+fq*8))
;   #define WAIT_V(n) asm volatile("s_waitcnt vmcnt(" #n ")":::"memory")
;   #define BAR __builtin_amdgcn_s_barrier()
;   #define SCHED __builtin_amdgcn_sched_barrier(0)
; template <class Pre, class Fin, class Epi> ...
;     ...
;   if(wr==1)BAR;
;   if (pf && pfE == 16)      { WAIT_V(26); BAR; WAIT_V(22); BAR; }
;   else if (pf && pfE == 32) { WAIT_V(42); BAR; WAIT_V(38); BAR; }
;   else                      { WAIT_V(10); BAR; WAIT_V(6); BAR; }
;   for(int t=0;t<nt-2;t+=2){
;     LDB(B0,0,0); SCHED; LDA(At,0,0); STAGEA(SA(1,1),brow+HALF,t+1);
.LBB0_593:
	s_andn2_b64 vcc, exec, s[46:47]
	s_cbranch_vccnz .LBB0_595
.LBB0_594:
	s_waitcnt vmcnt(26)
	s_barrier
	s_waitcnt vmcnt(22)
	s_barrier
.LBB0_595:
	v_and_b32_e32 v2, 15, v141
	v_lshlrev_b32_e32 v1, 6, v141
	v_and_b32_e32 v149, 0x3000, v1
	v_lshlrev_b32_e32 v1, 6, v2
	v_lshlrev_b32_e32 v2, 2, v2
	v_and_b32_e32 v0, 48, v141
	s_cmpk_gt_i32 s50, 0xbf
	s_mov_b64 s[48:49], -1
	v_or_b32_e32 v155, 0x400, v149
	v_or_b32_e32 v153, 0x800, v149
	v_or_b32_e32 v154, 0xc00, v149
	v_lshlrev_b32_e32 v166, 13, v3
	v_and_b32_e32 v2, 32, v2
	s_cbranch_scc1 .LBB0_597
	s_or_b32 s44, s40, 0x80
	v_lshlrev_b32_e32 v167, 13, v3
	s_ashr_i32 s45, s44, 31
	v_or_b32_e32 v129, 0x400, v149
	v_or_b32_e32 v131, 0x800, v149
	v_or_b32_e32 v133, 0xc00, v149
	v_bitop3_b32 v156, v1, v2, v0 bitop3:0x36
	v_or_b32_e32 v158, 0x400, v167
	v_or_b32_e32 v159, 0x800, v167
	v_or_b32_e32 v160, 0xc00, v167
	v_or_b32_e32 v161, 0x1000, v167
	v_or_b32_e32 v162, 0x1400, v167
	v_or_b32_e32 v163, 0x1800, v167
	v_or_b32_e32 v164, 0x1c00, v167
	s_lshl_b64 s[44:45], s[44:45], 11
	s_mov_b64 s[48:49], 0

; __device__ __forceinline__ u32x2 pack4(float a, float b, float c, float d) { return u32x2{cvtpk(a, b), cvtpk(c, d)}; }
; __device__ __forceinline__ u32x2 pack4(const f32x4& v) { return u32x2{cvtpk(v[0], v[1]), cvtpk(v[2], v[3])}; }
; #define SBAR() __builtin_amdgcn_sched_barrier(0)
; __global__ void __launch_bounds__(512) fwd_megakernel(Params p) {
;     ...
;         float* red = (float*)(shm_raw + EPI_LDS_OFF);
;         #pragma unroll
;         for (int ai = 0; ai < 2; ++ai)
;           #pragma unroll
;           for (int mp = 0; mp < 2; ++mp) { SBAR();
;             f32x4 xv[2][2][2];
;             #pragma unroll
;             for (int mm = 0; mm < 2; ++mm) {
;               const float* xr = xrow_ptr(p, brow + ai * 128 + wr * 64 + (mp * 2 + mm) * 16 + fr) + pn * 256 + wc * 32 + fq * 4;
;               #pragma unroll
;               for (int bj = 0; bj < 2; ++bj)
;                 #pragma unroll
;                 for (int n = 0; n < 2; ++n) xv[mm][bj][n] = *reinterpret_cast<const f32x4*>(xr + bj * 128 + n * 16);
;             }
;             SBAR();
;             #pragma unroll
;             for (int mm = 0; mm < 2; ++mm) {
;               const int m = mp * 2 + mm;
;               int lrow = ai * 128 + wr * 64 + m * 16 + fr, row = brow + lrow; float ss = 0.f;
;               bf16* hd = p_h1b + (long)row * DM + pn * 256 + wc * 32 + fq * 4;
;               #pragma unroll
;               for (int bj = 0; bj < 2; ++bj)
;                 #pragma unroll
;                 for (int n = 0; n < 2; ++n) {
;                   f32x4 v = acc[ai][bj][m][n] + xv[mm][bj][n];
;                   ss += (v[0] * v[0] + v[1] * v[1]) + (v[2] * v[2] + v[3] * v[3]);
;                   *reinterpret_cast<u32x2*>(hd + bj * 128 + n * 16) = pack4(v);
;                 }
;               ss += __shfl_xor(ss, 16); ss += __shfl_xor(ss, 32);
;               if (fq == 0) red[wc * 256 + lrow] = ss;
;             }
.LBB0_605:
	v_mov_b32_e32 v128, v252
	s_waitcnt lgkmcnt(0)
	s_barrier
	s_nop 0
	v_bfe_u32 v152, v128, 6, 2
	v_and_b32_e32 v129, 15, v128
	v_bfe_u32 v153, v128, 4, 2
	v_ashrrev_i32_e32 v128, 2, v128
	v_and_or_b32 v151, v128, s63, v129
	v_cmp_eq_u32_e32 vcc, 0, v153
	v_lshl_add_u32 v172, v152, 10, s69
	v_add_u32_e32 v148, s40, v151
	v_add_u32_e32 v128, 0xffff8000, v148
	v_ashrrev_i32_e32 v149, 31, v148
	v_cmp_gt_i32_e64 s[0:1], s60, v148
	v_mov_b32_e32 v132, s39
	v_mov_b32_e32 v133, s37
	v_cndmask_b32_e64 v129, 0, v149, s[0:1]
	v_cndmask_b32_e64 v128, v128, v148, s[0:1]
	v_mov_b32_e32 v134, s38
	v_mov_b32_e32 v135, s36
	s_ashr_i32 s43, s42, 31
	v_cndmask_b32_e64 v131, v132, v133, s[0:1]
	v_cndmask_b32_e64 v130, v134, v135, s[0:1]
	v_lshlrev_b64 v[128:129], 12, v[128:129]
	v_lshl_add_u64 v[128:129], v[130:131], 0, v[128:129]
	s_lshl_b64 s[44:45], s[42:43], 2
	v_lshl_add_u64 v[128:129], v[128:129], 0, s[44:45]
	v_lshlrev_b32_e32 v146, 7, v152
	v_lshl_add_u64 v[128:129], v[128:129], 0, v[146:147]
	v_lshlrev_b32_e32 v130, 4, v153
	v_mov_b32_e32 v131, v147
	v_lshl_add_u64 v[128:129], v[128:129], 0, v[130:131]
	global_load_dwordx4 v[154:157], v[128:129], off
	global_load_dwordx4 v[158:161], v[128:129], off offset:64
	global_load_dwordx4 v[162:165], v[128:129], off offset:512
	global_load_dwordx4 v[166:169], v[128:129], off offset:576
	v_or_b32_e32 v128, 16, v148
	v_add_u32_e32 v136, 0xffff8010, v148
	v_ashrrev_i32_e32 v129, 31, v128
	v_cmp_gt_i32_e64 s[0:1], s60, v128
	s_nop 1
	v_cndmask_b32_e64 v129, 0, v129, s[0:1]
	v_cndmask_b32_e64 v128, v136, v128, s[0:1]
	v_cndmask_b32_e64 v133, v132, v133, s[0:1]
	v_cndmask_b32_e64 v132, v134, v135, s[0:1]
	v_lshlrev_b64 v[128:129], 12, v[128:129]
	v_lshl_add_u64 v[128:129], v[132:133], 0, v[128:129]
	v_lshl_add_u64 v[128:129], v[128:129], 0, s[44:45]
	v_lshl_add_u64 v[128:129], v[128:129], 0, v[146:147]
	v_lshl_add_u64 v[128:129], v[128:129], 0, v[130:131]
	global_load_dwordx4 v[140:143], v[128:129], off
	global_load_dwordx4 v[136:139], v[128:129], off offset:64
	global_load_dwordx4 v[132:135], v[128:129], off offset:512
	s_nop 0
	global_load_dwordx4 v[128:131], v[128:129], off offset:576
	v_lshlrev_b64 v[170:171], 11, v[148:149]
	v_lshl_add_u64 v[170:171], s[26:27], 0, v[170:171]
	v_lshl_add_u64 v[170:171], s[42:43], 1, v[170:171]
	v_lshlrev_b32_e32 v146, 6, v152
	v_lshl_add_u64 v[170:171], v[170:171], 0, v[146:147]
	v_lshlrev_b32_e32 v146, 3, v153
	s_waitcnt vmcnt(0)
	v_pk_add_f32 v[124:125], v[124:125], v[154:155]
	v_lshl_add_u64 v[170:171], v[170:171], 0, v[146:147]
	v_mul_f32_e32 v146, v125, v125
	v_pk_add_f32 v[126:127], v[126:127], v[156:157]
	v_fmac_f32_e32 v146, v124, v124
	v_cvt_pk_bf16_f32 v124, v124, v125
	v_cvt_pk_bf16_f32 v125, v126, v127
	v_pk_add_f32 v[118:119], v[118:119], v[160:161]
	v_pk_add_f32 v[116:117], v[116:117], v[158:159]
	v_mul_f32_e32 v149, v127, v127
	v_mov_b32_e32 v196, v124
	v_mov_b32_e32 v197, v125
	v_mul_f32_e32 v124, v117, v117
	v_mul_f32_e32 v125, v119, v119
	v_pk_add_f32 v[122:123], v[122:123], v[164:165]
	v_pk_add_f32 v[120:121], v[120:121], v[162:163]
	v_fmac_f32_e32 v149, v126, v126
	v_fmac_f32_e32 v124, v116, v116
	v_fmac_f32_e32 v125, v118, v118
	v_cvt_pk_bf16_f32 v116, v116, v117
	v_cvt_pk_bf16_f32 v117, v118, v119
	v_mul_f32_e32 v118, v121, v121
	v_mul_f32_e32 v119, v123, v123
	v_add_f32_e32 v146, v146, v149
	v_add_f32_e32 v124, v124, v125
	v_fmac_f32_e32 v118, v120, v120
	v_fmac_f32_e32 v119, v122, v122
	v_add_f32_e32 v124, v146, v124
	v_add_f32_e32 v118, v118, v119
	v_add_f32_e32 v118, v124, v118
	v_pk_add_f32 v[114:115], v[114:115], v[168:169]
	v_pk_add_f32 v[124:125], v[112:113], v[166:167]
	v_mul_f32_e32 v113, v115, v115
	v_mul_f32_e32 v112, v125, v125
	v_fmac_f32_e32 v112, v124, v124
	v_fmac_f32_e32 v113, v114, v114
	v_add_f32_e32 v112, v112, v113
	v_and_b32_e32 v113, 64, v145
	v_add_f32_e32 v118, v118, v112
	v_xor_b32_e32 v112, 16, v145
	v_add_u32_e32 v126, 64, v113
	v_cmp_lt_i32_e64 s[0:1], v112, v126
	v_mov_b32_e32 v198, v116
	v_mov_b32_e32 v199, v117
	v_bfe_u32 v194, v252, 4, 1
	v_mul_u32_u24_e32 v194, 24, v194
	v_mov_b32_e32 v195, 0
	v_lshl_add_u64 v[200:201], v[170:171], 0, v[194:195]
	v_permlane16_swap_b32_e32 v196, v198
	v_permlane16_swap_b32_e32 v197, v199
	global_store_dwordx4 v[200:201], v[196:199], off
	s_nop 1
	s_nop 0
	v_cndmask_b32_e64 v112, v145, v112, s[0:1]
	v_lshlrev_b32_e32 v119, 2, v112
	ds_bpermute_b32 v127, v119, v118
	v_cvt_pk_bf16_f32 v112, v120, v121
	v_cvt_pk_bf16_f32 v113, v122, v123
	v_mov_b32_e32 v196, v112
	v_mov_b32_e32 v197, v113
	v_xor_b32_e32 v113, 32, v145
	v_cmp_lt_i32_e64 s[0:1], v113, v126
	s_waitcnt lgkmcnt(0)
	v_add_f32_e32 v112, v118, v127
	v_lshl_add_u32 v118, v151, 2, v172
	v_cndmask_b32_e64 v113, v145, v113, s[0:1]
	v_lshlrev_b32_e32 v120, 2, v113
	ds_bpermute_b32 v113, v120, v112
	v_cvt_pk_bf16_f32 v116, v124, v125
	v_cvt_pk_bf16_f32 v117, v114, v115
	v_mov_b32_e32 v198, v116
	v_mov_b32_e32 v199, v117
	v_bfe_u32 v194, v252, 4, 1
	v_mul_u32_u24_e32 v194, 24, v194
	v_mov_b32_e32 v195, 0
	v_lshl_add_u64 v[200:201], v[170:171], 0, v[194:195]
	v_permlane16_swap_b32_e32 v196, v198
	v_permlane16_swap_b32_e32 v197, v199
	global_store_dwordx4 v[200:201], v[196:199], off offset:256
	s_nop 1
	s_and_saveexec_b64 s[0:1], vcc
	s_cbranch_execz .LBB0_607
	s_waitcnt lgkmcnt(0)
	v_add_f32_e32 v112, v112, v113
	ds_write_b32 v118, v112
; __device__ __forceinline__ u32x2 pack4(float a, float b, float c, float d) { return u32x2{cvtpk(a, b), cvtpk(c, d)}; }
; __device__ __forceinline__ u32x2 pack4(const f32x4& v) { return u32x2{cvtpk(v[0], v[1]), cvtpk(v[2], v[3])}; }
; #define SBAR() __builtin_amdgcn_sched_barrier(0)
; __global__ void __launch_bounds__(512) fwd_megakernel(Params p) {
;     ...
;             for (int mm = 0; mm < 2; ++mm) {
;               const float* xr = xrow_ptr(p, brow + ai * 128 + wr * 64 + (mp * 2 + mm) * 16 + fr) + pn * 256 + wc * 32 + fq * 4;
;               #pragma unroll
;               for (int bj = 0; bj < 2; ++bj)
;                 #pragma unroll
;                 for (int n = 0; n < 2; ++n) xv[mm][bj][n] = *reinterpret_cast<const f32x4*>(xr + bj * 128 + n * 16);
;             }
;             SBAR();
;             #pragma unroll
;             for (int mm = 0; mm < 2; ++mm) {
;               const int m = mp * 2 + mm;
;               int lrow = ai * 128 + wr * 64 + m * 16 + fr, row = brow + lrow; float ss = 0.f;
;               bf16* hd = p_h1b + (long)row * DM + pn * 256 + wc * 32 + fq * 4;
;               #pragma unroll
;               for (int bj = 0; bj < 2; ++bj)
;                 #pragma unroll
;                 for (int n = 0; n < 2; ++n) {
;                   f32x4 v = acc[ai][bj][m][n] + xv[mm][bj][n];
;                   ss += (v[0] * v[0] + v[1] * v[1]) + (v[2] * v[2] + v[3] * v[3]);
;                   *reinterpret_cast<u32x2*>(hd + bj * 128 + n * 16) = pack4(v);
;                 }
;               ss += __shfl_xor(ss, 16); ss += __shfl_xor(ss, 32);
;               if (fq == 0) red[wc * 256 + lrow] = ss;
;             }
.LBB0_607:
	s_or_b64 exec, exec, s[0:1]
	v_add3_u32 v112, s40, v151, 16
	s_waitcnt lgkmcnt(0)
	v_ashrrev_i32_e32 v113, 31, v112
	v_lshlrev_b64 v[112:113], 11, v[112:113]
	v_lshlrev_b32_e32 v114, 5, v152
	v_lshl_add_u64 v[112:113], s[26:27], 0, v[112:113]
	v_lshlrev_b32_e32 v116, 2, v153
	v_lshl_add_u64 v[112:113], s[42:43], 1, v[112:113]
	v_lshlrev_b32_e32 v146, 1, v114
	v_pk_add_f32 v[108:109], v[108:109], v[140:141]
	v_lshl_add_u64 v[122:123], v[112:113], 0, v[146:147]
	v_lshlrev_b32_e32 v112, 1, v116
	v_mov_b32_e32 v113, v147
	v_mul_f32_e32 v115, v109, v109
	v_lshl_add_u64 v[122:123], v[122:123], 0, v[112:113]
	v_pk_add_f32 v[110:111], v[110:111], v[142:143]
	v_fmac_f32_e32 v115, v108, v108
	v_cvt_pk_bf16_f32 v108, v108, v109
	v_cvt_pk_bf16_f32 v109, v110, v111
	v_pk_add_f32 v[102:103], v[102:103], v[138:139]
	v_pk_add_f32 v[100:101], v[100:101], v[136:137]
	v_mov_b32_e32 v196, v108
	v_mov_b32_e32 v197, v109
	v_mul_f32_e32 v108, v101, v101
	v_mul_f32_e32 v109, v103, v103
	v_mul_f32_e32 v117, v111, v111
	v_fmac_f32_e32 v108, v100, v100
	v_fmac_f32_e32 v109, v102, v102
	v_pk_add_f32 v[106:107], v[106:107], v[134:135]
	v_pk_add_f32 v[104:105], v[104:105], v[132:133]
	v_fmac_f32_e32 v117, v110, v110
	v_add_f32_e32 v108, v108, v109
	v_cvt_pk_bf16_f32 v100, v100, v101
	v_mul_f32_e32 v101, v105, v105
	v_mul_f32_e32 v109, v107, v107
	v_add_f32_e32 v115, v115, v117
	v_fmac_f32_e32 v101, v104, v104
	v_fmac_f32_e32 v109, v106, v106
	v_add_f32_e32 v108, v115, v108
	v_add_f32_e32 v101, v101, v109
	v_add_f32_e32 v101, v108, v101
	v_pk_add_f32 v[98:99], v[98:99], v[130:131]
	v_pk_add_f32 v[108:109], v[96:97], v[128:129]
	v_mul_f32_e32 v97, v99, v99
	v_mul_f32_e32 v96, v109, v109
	v_fmac_f32_e32 v96, v108, v108
	v_fmac_f32_e32 v97, v98, v98
	v_add_f32_e32 v96, v96, v97
	v_add_f32_e32 v96, v101, v96
	ds_bpermute_b32 v97, v119, v96
	v_cvt_pk_bf16_f32 v101, v102, v103
	v_mov_b32_e32 v198, v100
	v_mov_b32_e32 v199, v101
	v_bfe_u32 v194, v252, 4, 1
	v_mul_u32_u24_e32 v194, 24, v194
	v_mov_b32_e32 v195, 0
	v_lshl_add_u64 v[200:201], v[122:123], 0, v[194:195]
	v_permlane16_swap_b32_e32 v196, v198
	v_permlane16_swap_b32_e32 v197, v199
	global_store_dwordx4 v[200:201], v[196:199], off
	s_nop 1
	v_cvt_pk_bf16_f32 v100, v104, v105
	v_cvt_pk_bf16_f32 v101, v106, v107
	s_waitcnt lgkmcnt(0)
	v_add_f32_e32 v96, v96, v97
	ds_bpermute_b32 v97, v120, v96
	v_mov_b32_e32 v196, v100
	v_mov_b32_e32 v197, v101
	v_cvt_pk_bf16_f32 v100, v108, v109
	v_cvt_pk_bf16_f32 v101, v98, v99
	v_mov_b32_e32 v198, v100
	v_mov_b32_e32 v199, v101
	v_bfe_u32 v194, v252, 4, 1
	v_mul_u32_u24_e32 v194, 24, v194
	v_mov_b32_e32 v195, 0
	v_lshl_add_u64 v[200:201], v[122:123], 0, v[194:195]
	v_permlane16_swap_b32_e32 v196, v198
	v_permlane16_swap_b32_e32 v197, v199
	global_store_dwordx4 v[200:201], v[196:199], off offset:256
	s_nop 1
	s_and_saveexec_b64 s[0:1], vcc
	s_cbranch_execz .LBB0_609
	s_waitcnt lgkmcnt(0)
	v_add_f32_e32 v96, v96, v97
	ds_write_b32 v118, v96 offset:64
.LBB0_609:
	s_or_b64 exec, exec, s[0:1]
	v_add_u32_e32 v138, 32, v148
	v_add_u32_e32 v96, 0xffff8020, v148
	v_ashrrev_i32_e32 v139, 31, v138
	v_cmp_gt_i32_e64 s[0:1], s60, v138
	v_mov_b32_e32 v100, s39
	v_mov_b32_e32 v101, s37
	s_waitcnt lgkmcnt(0)
	v_cndmask_b32_e64 v97, 0, v139, s[0:1]
	v_cndmask_b32_e64 v96, v96, v138, s[0:1]
	v_mov_b32_e32 v102, s38
	v_mov_b32_e32 v103, s36
	v_cndmask_b32_e64 v99, v100, v101, s[0:1]
	v_cndmask_b32_e64 v98, v102, v103, s[0:1]
	v_lshlrev_b64 v[96:97], 12, v[96:97]
	v_lshl_add_u64 v[96:97], v[98:99], 0, v[96:97]
	v_lshl_add_u64 v[96:97], v[96:97], 0, s[44:45]
	v_lshlrev_b32_e32 v114, 2, v114
	v_mov_b32_e32 v115, v147
	v_lshl_add_u64 v[96:97], v[96:97], 0, v[114:115]
	v_lshlrev_b32_e32 v116, 2, v116
	v_mov_b32_e32 v117, v147
	v_lshl_add_u64 v[96:97], v[96:97], 0, v[116:117]
	global_load_dwordx4 v[122:125], v[96:97], off
	global_load_dwordx4 v[126:129], v[96:97], off offset:64
	global_load_dwordx4 v[130:133], v[96:97], off offset:512
	global_load_dwordx4 v[134:137], v[96:97], off offset:576
	v_add_u32_e32 v96, 48, v148
	v_add_u32_e32 v98, 0xffff8030, v148
	v_ashrrev_i32_e32 v97, 31, v96
	v_cmp_gt_i32_e64 s[0:1], s60, v96
	s_nop 1
	v_cndmask_b32_e64 v97, 0, v97, s[0:1]
	v_cndmask_b32_e64 v96, v98, v96, s[0:1]
	v_cndmask_b32_e64 v99, v100, v101, s[0:1]
	v_cndmask_b32_e64 v98, v102, v103, s[0:1]
	v_lshlrev_b64 v[96:97], 12, v[96:97]
	v_lshl_add_u64 v[96:97], v[98:99], 0, v[96:97]
	v_lshl_add_u64 v[96:97], v[96:97], 0, s[44:45]
	v_lshl_add_u64 v[96:97], v[96:97], 0, v[114:115]
	v_lshl_add_u64 v[96:97], v[96:97], 0, v[116:117]
	global_load_dwordx4 v[108:111], v[96:97], off
	global_load_dwordx4 v[104:107], v[96:97], off offset:64
	global_load_dwordx4 v[100:103], v[96:97], off offset:512
	s_nop 0
	global_load_dwordx4 v[96:99], v[96:97], off offset:576
	v_lshlrev_b64 v[138:139], 11, v[138:139]
	v_lshl_add_u64 v[138:139], s[26:27], 0, v[138:139]
	v_lshl_add_u64 v[138:139], s[42:43], 1, v[138:139]
	v_lshl_add_u64 v[138:139], v[138:139], 0, v[146:147]
	s_waitcnt vmcnt(7)
	v_pk_add_f32 v[92:93], v[92:93], v[122:123]
	v_lshl_add_u64 v[138:139], v[138:139], 0, v[112:113]
	v_mul_f32_e32 v113, v93, v93
	v_pk_add_f32 v[94:95], v[94:95], v[124:125]
	v_fmac_f32_e32 v113, v92, v92
	v_cvt_pk_bf16_f32 v92, v92, v93
	v_cvt_pk_bf16_f32 v93, v94, v95
	s_waitcnt vmcnt(6)
	v_pk_add_f32 v[86:87], v[86:87], v[128:129]
	v_pk_add_f32 v[84:85], v[84:85], v[126:127]
	v_mov_b32_e32 v196, v92
	v_mov_b32_e32 v197, v93
	v_mul_f32_e32 v92, v85, v85
	v_mul_f32_e32 v93, v87, v87
	v_mul_f32_e32 v115, v95, v95
	v_fmac_f32_e32 v92, v84, v84
	v_fmac_f32_e32 v93, v86, v86
	s_waitcnt vmcnt(5)
; __device__ __forceinline__ u32x2 pack4(float a, float b, float c, float d) { return u32x2{cvtpk(a, b), cvtpk(c, d)}; }
; __device__ __forceinline__ u32x2 pack4(const f32x4& v) { return u32x2{cvtpk(v[0], v[1]), cvtpk(v[2], v[3])}; }
; __global__ void __launch_bounds__(512) fwd_megakernel(Params p) {
;     ...
;             for (int mm = 0; mm < 2; ++mm) {
;               const int m = mp * 2 + mm;
;               int lrow = ai * 128 + wr * 64 + m * 16 + fr, row = brow + lrow; float ss = 0.f;
;               bf16* hd = p_h1b + (long)row * DM + pn * 256 + wc * 32 + fq * 4;
;               #pragma unroll
;               for (int bj = 0; bj < 2; ++bj)
;                 #pragma unroll
;                 for (int n = 0; n < 2; ++n) {
;                   f32x4 v = acc[ai][bj][m][n] + xv[mm][bj][n];
;                   ss += (v[0] * v[0] + v[1] * v[1]) + (v[2] * v[2] + v[3] * v[3]);
;                   *reinterpret_cast<u32x2*>(hd + bj * 128 + n * 16) = pack4(v);
;                 }
;               ss += __shfl_xor(ss, 16); ss += __shfl_xor(ss, 32);
;               if (fq == 0) red[wc * 256 + lrow] = ss;
;             }
	v_pk_add_f32 v[90:91], v[90:91], v[132:133]
	v_pk_add_f32 v[88:89], v[88:89], v[130:131]
	v_fmac_f32_e32 v115, v94, v94
	v_add_f32_e32 v92, v92, v93
	v_cvt_pk_bf16_f32 v84, v84, v85
	v_mul_f32_e32 v85, v89, v89
	v_mul_f32_e32 v93, v91, v91
	v_add_f32_e32 v113, v113, v115
	v_fmac_f32_e32 v85, v88, v88
	v_fmac_f32_e32 v93, v90, v90
	v_add_f32_e32 v92, v113, v92
	v_add_f32_e32 v85, v85, v93
	v_add_f32_e32 v85, v92, v85
	s_waitcnt vmcnt(4)
	v_pk_add_f32 v[82:83], v[82:83], v[136:137]
	v_pk_add_f32 v[92:93], v[80:81], v[134:135]
	v_mul_f32_e32 v81, v83, v83
	v_mul_f32_e32 v80, v93, v93
	v_fmac_f32_e32 v80, v92, v92
	v_fmac_f32_e32 v81, v82, v82
	v_add_f32_e32 v80, v80, v81
	v_add_f32_e32 v80, v85, v80
	ds_bpermute_b32 v81, v119, v80
	v_cvt_pk_bf16_f32 v85, v86, v87
	v_mov_b32_e32 v198, v84
	v_mov_b32_e32 v199, v85
	v_bfe_u32 v194, v252, 4, 1
	v_mul_u32_u24_e32 v194, 24, v194
	v_mov_b32_e32 v195, 0
	v_lshl_add_u64 v[200:201], v[138:139], 0, v[194:195]
	v_permlane16_swap_b32_e32 v196, v198
	v_permlane16_swap_b32_e32 v197, v199
	global_store_dwordx4 v[200:201], v[196:199], off
	s_nop 1
	v_cvt_pk_bf16_f32 v84, v88, v89
	v_cvt_pk_bf16_f32 v85, v90, v91
	s_waitcnt lgkmcnt(0)
	v_add_f32_e32 v80, v80, v81
	ds_bpermute_b32 v81, v120, v80
	v_mov_b32_e32 v196, v84
	v_mov_b32_e32 v197, v85
	v_cvt_pk_bf16_f32 v84, v92, v93
	v_cvt_pk_bf16_f32 v85, v82, v83
	v_mov_b32_e32 v198, v84
	v_mov_b32_e32 v199, v85
	v_bfe_u32 v194, v252, 4, 1
	v_mul_u32_u24_e32 v194, 24, v194
	v_mov_b32_e32 v195, 0
	v_lshl_add_u64 v[200:201], v[138:139], 0, v[194:195]
	v_permlane16_swap_b32_e32 v196, v198
	v_permlane16_swap_b32_e32 v197, v199
	global_store_dwordx4 v[200:201], v[196:199], off offset:256
	s_nop 1
	s_and_saveexec_b64 s[0:1], vcc
	s_cbranch_execz .LBB0_611
	s_waitcnt lgkmcnt(0)
	v_add_f32_e32 v80, v80, v81
	ds_write_b32 v118, v80 offset:128
.LBB0_611:
	s_or_b64 exec, exec, s[0:1]
	v_add3_u32 v80, s40, v151, 48
	s_waitcnt lgkmcnt(0)
	v_ashrrev_i32_e32 v81, 31, v80
	v_lshlrev_b64 v[80:81], 11, v[80:81]
	v_lshl_add_u64 v[80:81], s[26:27], 0, v[80:81]
	v_lshl_add_u64 v[80:81], s[42:43], 1, v[80:81]
	s_waitcnt vmcnt(5)
	v_pk_add_f32 v[76:77], v[76:77], v[108:109]
	v_lshl_add_u64 v[80:81], v[80:81], 0, v[146:147]
	v_mov_b32_e32 v113, v147
	v_mul_f32_e32 v82, v77, v77
	v_lshl_add_u64 v[80:81], v[80:81], 0, v[112:113]
	v_pk_add_f32 v[78:79], v[78:79], v[110:111]
	v_fmac_f32_e32 v82, v76, v76
	v_cvt_pk_bf16_f32 v76, v76, v77
	v_cvt_pk_bf16_f32 v77, v78, v79
	s_waitcnt vmcnt(4)
	v_pk_add_f32 v[70:71], v[70:71], v[106:107]
	v_pk_add_f32 v[68:69], v[68:69], v[104:105]
	v_mov_b32_e32 v196, v76
	v_mov_b32_e32 v197, v77
	v_mul_f32_e32 v76, v69, v69
	v_mul_f32_e32 v77, v71, v71
	v_mul_f32_e32 v83, v79, v79
	v_fmac_f32_e32 v76, v68, v68
	v_fmac_f32_e32 v77, v70, v70
	s_waitcnt vmcnt(3)
	v_pk_add_f32 v[74:75], v[74:75], v[102:103]
	v_pk_add_f32 v[72:73], v[72:73], v[100:101]
	v_fmac_f32_e32 v83, v78, v78
	v_add_f32_e32 v76, v76, v77
	v_cvt_pk_bf16_f32 v68, v68, v69
	v_mul_f32_e32 v69, v73, v73
	v_mul_f32_e32 v77, v75, v75
	v_add_f32_e32 v82, v82, v83
	v_fmac_f32_e32 v69, v72, v72
	v_fmac_f32_e32 v77, v74, v74
	v_add_f32_e32 v76, v82, v76
	v_add_f32_e32 v69, v69, v77
	v_add_f32_e32 v69, v76, v69
	s_waitcnt vmcnt(2)
	v_pk_add_f32 v[66:67], v[66:67], v[98:99]
	v_pk_add_f32 v[76:77], v[64:65], v[96:97]
	v_mul_f32_e32 v65, v67, v67
	v_mul_f32_e32 v64, v77, v77
	v_fmac_f32_e32 v64, v76, v76
	v_fmac_f32_e32 v65, v66, v66
	v_add_f32_e32 v64, v64, v65
	v_add_f32_e32 v64, v69, v64
	ds_bpermute_b32 v65, v119, v64
	v_cvt_pk_bf16_f32 v69, v70, v71
	v_mov_b32_e32 v198, v68
	v_mov_b32_e32 v199, v69
	v_bfe_u32 v194, v252, 4, 1
	v_mul_u32_u24_e32 v194, 24, v194
	v_mov_b32_e32 v195, 0
	v_lshl_add_u64 v[200:201], v[80:81], 0, v[194:195]
	v_permlane16_swap_b32_e32 v196, v198
	v_permlane16_swap_b32_e32 v197, v199
	global_store_dwordx4 v[200:201], v[196:199], off
	s_nop 1
	v_cvt_pk_bf16_f32 v68, v72, v73
	v_cvt_pk_bf16_f32 v69, v74, v75
	s_waitcnt lgkmcnt(0)
	v_add_f32_e32 v64, v64, v65
	ds_bpermute_b32 v65, v120, v64
	v_mov_b32_e32 v196, v68
	v_mov_b32_e32 v197, v69
	v_cvt_pk_bf16_f32 v68, v76, v77
	v_cvt_pk_bf16_f32 v69, v66, v67
	v_mov_b32_e32 v198, v68
	v_mov_b32_e32 v199, v69
	v_bfe_u32 v194, v252, 4, 1
	v_mul_u32_u24_e32 v194, 24, v194
	v_mov_b32_e32 v195, 0
	v_lshl_add_u64 v[200:201], v[80:81], 0, v[194:195]
	v_permlane16_swap_b32_e32 v196, v198
	v_permlane16_swap_b32_e32 v197, v199
	global_store_dwordx4 v[200:201], v[196:199], off offset:256
	s_nop 1
	s_and_saveexec_b64 s[0:1], vcc
	s_cbranch_execz .LBB0_613
	s_waitcnt lgkmcnt(0)
	v_add_f32_e32 v64, v64, v65
	ds_write_b32 v118, v64 offset:192
; __device__ __forceinline__ u32x2 pack4(float a, float b, float c, float d) { return u32x2{cvtpk(a, b), cvtpk(c, d)}; }
; __device__ __forceinline__ u32x2 pack4(const f32x4& v) { return u32x2{cvtpk(v[0], v[1]), cvtpk(v[2], v[3])}; }
; #define SBAR() __builtin_amdgcn_sched_barrier(0)
; __global__ void __launch_bounds__(512) fwd_megakernel(Params p) {
;     ...
;         for (int ai = 0; ai < 2; ++ai)
;           #pragma unroll
;           for (int mp = 0; mp < 2; ++mp) { SBAR();
;             f32x4 xv[2][2][2];
;             #pragma unroll
;             for (int mm = 0; mm < 2; ++mm) {
;               const float* xr = xrow_ptr(p, brow + ai * 128 + wr * 64 + (mp * 2 + mm) * 16 + fr) + pn * 256 + wc * 32 + fq * 4;
;               #pragma unroll
;               for (int bj = 0; bj < 2; ++bj)
;                 #pragma unroll
;                 for (int n = 0; n < 2; ++n) xv[mm][bj][n] = *reinterpret_cast<const f32x4*>(xr + bj * 128 + n * 16);
;             }
;             SBAR();
;             #pragma unroll
;             for (int mm = 0; mm < 2; ++mm) {
;               const int m = mp * 2 + mm;
;               int lrow = ai * 128 + wr * 64 + m * 16 + fr, row = brow + lrow; float ss = 0.f;
;               bf16* hd = p_h1b + (long)row * DM + pn * 256 + wc * 32 + fq * 4;
;               #pragma unroll
;               for (int bj = 0; bj < 2; ++bj)
;                 #pragma unroll
;                 for (int n = 0; n < 2; ++n) {
;                   f32x4 v = acc[ai][bj][m][n] + xv[mm][bj][n];
;                   ss += (v[0] * v[0] + v[1] * v[1]) + (v[2] * v[2] + v[3] * v[3]);
;                   *reinterpret_cast<u32x2*>(hd + bj * 128 + n * 16) = pack4(v);
;                 }
;               ss += __shfl_xor(ss, 16); ss += __shfl_xor(ss, 32);
;               if (fq == 0) red[wc * 256 + lrow] = ss;
;             }
.LBB0_613:
	s_or_b64 exec, exec, s[0:1]
	v_add_u32_e32 v98, 0x80, v148
	v_add_u32_e32 v64, 0xffff8080, v148
	v_ashrrev_i32_e32 v99, 31, v98
	v_cmp_gt_i32_e64 s[0:1], s60, v98
	v_mov_b32_e32 v68, s39
	v_mov_b32_e32 v69, s37
	s_waitcnt lgkmcnt(0)
	v_cndmask_b32_e64 v65, 0, v99, s[0:1]
	v_cndmask_b32_e64 v64, v64, v98, s[0:1]
	v_mov_b32_e32 v70, s38
	v_mov_b32_e32 v71, s36
	v_cndmask_b32_e64 v67, v68, v69, s[0:1]
	v_cndmask_b32_e64 v66, v70, v71, s[0:1]
	v_lshlrev_b64 v[64:65], 12, v[64:65]
	v_lshl_add_u64 v[64:65], v[66:67], 0, v[64:65]
	v_lshl_add_u64 v[64:65], v[64:65], 0, s[44:45]
	v_mov_b32_e32 v115, v147
	v_lshl_add_u64 v[64:65], v[64:65], 0, v[114:115]
	v_mov_b32_e32 v117, v147
	v_lshl_add_u64 v[64:65], v[64:65], 0, v[116:117]
	v_add_u32_e32 v80, 0x90, v148
	global_load_dwordx4 v[82:85], v[64:65], off
	global_load_dwordx4 v[86:89], v[64:65], off offset:64
	global_load_dwordx4 v[90:93], v[64:65], off offset:512
	global_load_dwordx4 v[94:97], v[64:65], off offset:576
	v_add_u32_e32 v64, 0xffff8090, v148
	v_ashrrev_i32_e32 v81, 31, v80
	v_cmp_gt_i32_e64 s[0:1], s60, v80
	s_nop 1
	v_cndmask_b32_e64 v65, 0, v81, s[0:1]
	v_cndmask_b32_e64 v64, v64, v80, s[0:1]
	v_cndmask_b32_e64 v67, v68, v69, s[0:1]
	v_cndmask_b32_e64 v66, v70, v71, s[0:1]
	v_lshlrev_b64 v[64:65], 12, v[64:65]
	v_lshl_add_u64 v[64:65], v[66:67], 0, v[64:65]
	v_lshl_add_u64 v[64:65], v[64:65], 0, s[44:45]
	v_lshl_add_u64 v[64:65], v[64:65], 0, v[114:115]
	v_lshl_add_u64 v[64:65], v[64:65], 0, v[116:117]
	global_load_dwordx4 v[76:79], v[64:65], off
	global_load_dwordx4 v[72:75], v[64:65], off offset:64
	global_load_dwordx4 v[68:71], v[64:65], off offset:512
	s_nop 0
	global_load_dwordx4 v[64:67], v[64:65], off offset:576
	v_lshlrev_b64 v[98:99], 11, v[98:99]
	v_lshl_add_u64 v[98:99], s[26:27], 0, v[98:99]
	v_lshl_add_u64 v[98:99], s[42:43], 1, v[98:99]
	s_waitcnt vmcnt(7)
	v_pk_add_f32 v[60:61], v[60:61], v[82:83]
	v_lshl_add_u64 v[98:99], v[98:99], 0, v[146:147]
	v_mul_f32_e32 v82, v61, v61
	v_lshl_add_u64 v[98:99], v[98:99], 0, v[112:113]
	v_pk_add_f32 v[62:63], v[62:63], v[84:85]
	v_fmac_f32_e32 v82, v60, v60
	v_cvt_pk_bf16_f32 v60, v60, v61
	v_cvt_pk_bf16_f32 v61, v62, v63
	s_waitcnt vmcnt(6)
	v_pk_add_f32 v[58:59], v[58:59], v[88:89]
	v_pk_add_f32 v[56:57], v[56:57], v[86:87]
	v_mov_b32_e32 v196, v60
	v_mov_b32_e32 v197, v61
	v_mul_f32_e32 v60, v57, v57
	v_mul_f32_e32 v61, v59, v59
	v_mul_f32_e32 v83, v63, v63
	v_fmac_f32_e32 v60, v56, v56
	v_fmac_f32_e32 v61, v58, v58
	s_waitcnt vmcnt(5)
	v_pk_add_f32 v[54:55], v[54:55], v[92:93]
	v_pk_add_f32 v[52:53], v[52:53], v[90:91]
	v_fmac_f32_e32 v83, v62, v62
	v_add_f32_e32 v60, v60, v61
	v_cvt_pk_bf16_f32 v56, v56, v57
	v_mul_f32_e32 v57, v53, v53
	v_mul_f32_e32 v61, v55, v55
	v_add_f32_e32 v82, v82, v83
	v_fmac_f32_e32 v57, v52, v52
	v_fmac_f32_e32 v61, v54, v54
	v_add_f32_e32 v60, v82, v60
	v_add_f32_e32 v57, v57, v61
	v_add_f32_e32 v57, v60, v57
	s_waitcnt vmcnt(4)
	v_pk_add_f32 v[50:51], v[50:51], v[96:97]
	v_pk_add_f32 v[60:61], v[48:49], v[94:95]
	v_mul_f32_e32 v49, v51, v51
	v_mul_f32_e32 v48, v61, v61
	v_fmac_f32_e32 v48, v60, v60
	v_fmac_f32_e32 v49, v50, v50
	v_add_f32_e32 v48, v48, v49
	v_add_f32_e32 v48, v57, v48
	ds_bpermute_b32 v49, v119, v48
	v_cvt_pk_bf16_f32 v57, v58, v59
	v_mov_b32_e32 v198, v56
	v_mov_b32_e32 v199, v57
	v_bfe_u32 v194, v252, 4, 1
	v_mul_u32_u24_e32 v194, 24, v194
	v_mov_b32_e32 v195, 0
	v_lshl_add_u64 v[200:201], v[98:99], 0, v[194:195]
	v_permlane16_swap_b32_e32 v196, v198
	v_permlane16_swap_b32_e32 v197, v199
	global_store_dwordx4 v[200:201], v[196:199], off
	s_nop 1
	v_cvt_pk_bf16_f32 v52, v52, v53
	v_cvt_pk_bf16_f32 v53, v54, v55
	s_waitcnt lgkmcnt(0)
	v_add_f32_e32 v48, v48, v49
	ds_bpermute_b32 v49, v120, v48
	v_mov_b32_e32 v196, v52
	v_mov_b32_e32 v197, v53
	v_cvt_pk_bf16_f32 v52, v60, v61
	v_cvt_pk_bf16_f32 v53, v50, v51
	v_mov_b32_e32 v198, v52
	v_mov_b32_e32 v199, v53
	v_bfe_u32 v194, v252, 4, 1
	v_mul_u32_u24_e32 v194, 24, v194
	v_mov_b32_e32 v195, 0
	v_lshl_add_u64 v[200:201], v[98:99], 0, v[194:195]
	v_permlane16_swap_b32_e32 v196, v198
	v_permlane16_swap_b32_e32 v197, v199
	global_store_dwordx4 v[200:201], v[196:199], off offset:256
	s_nop 1
	s_and_saveexec_b64 s[0:1], vcc
	s_cbranch_execz .LBB0_615
	s_waitcnt lgkmcnt(0)
	v_add_f32_e32 v48, v48, v49
	ds_write_b32 v118, v48 offset:512
; __device__ __forceinline__ u32x2 pack4(float a, float b, float c, float d) { return u32x2{cvtpk(a, b), cvtpk(c, d)}; }
; __device__ __forceinline__ u32x2 pack4(const f32x4& v) { return u32x2{cvtpk(v[0], v[1]), cvtpk(v[2], v[3])}; }
; __global__ void __launch_bounds__(512) fwd_megakernel(Params p) {
;     ...
;             for (int mm = 0; mm < 2; ++mm) {
;               const int m = mp * 2 + mm;
;               int lrow = ai * 128 + wr * 64 + m * 16 + fr, row = brow + lrow; float ss = 0.f;
;               bf16* hd = p_h1b + (long)row * DM + pn * 256 + wc * 32 + fq * 4;
;               #pragma unroll
;               for (int bj = 0; bj < 2; ++bj)
;                 #pragma unroll
;                 for (int n = 0; n < 2; ++n) {
;                   f32x4 v = acc[ai][bj][m][n] + xv[mm][bj][n];
;                   ss += (v[0] * v[0] + v[1] * v[1]) + (v[2] * v[2] + v[3] * v[3]);
;                   *reinterpret_cast<u32x2*>(hd + bj * 128 + n * 16) = pack4(v);
;                 }
;               ss += __shfl_xor(ss, 16); ss += __shfl_xor(ss, 32);
;               if (fq == 0) red[wc * 256 + lrow] = ss;
;             }
.LBB0_615:
	s_or_b64 exec, exec, s[0:1]
	s_waitcnt lgkmcnt(0)
	v_lshlrev_b64 v[48:49], 11, v[80:81]
	v_lshl_add_u64 v[48:49], s[26:27], 0, v[48:49]
	v_lshl_add_u64 v[48:49], s[42:43], 1, v[48:49]
	s_waitcnt vmcnt(5)
	v_pk_add_f32 v[44:45], v[44:45], v[76:77]
	v_lshl_add_u64 v[48:49], v[48:49], 0, v[146:147]
	v_mov_b32_e32 v113, v147
	v_mul_f32_e32 v50, v45, v45
	v_lshl_add_u64 v[48:49], v[48:49], 0, v[112:113]
	v_pk_add_f32 v[46:47], v[46:47], v[78:79]
	v_fmac_f32_e32 v50, v44, v44
	v_cvt_pk_bf16_f32 v44, v44, v45
	v_cvt_pk_bf16_f32 v45, v46, v47
	s_waitcnt vmcnt(4)
	v_pk_add_f32 v[42:43], v[42:43], v[74:75]
	v_pk_add_f32 v[40:41], v[40:41], v[72:73]
	v_mov_b32_e32 v196, v44
	v_mov_b32_e32 v197, v45
	v_mul_f32_e32 v44, v41, v41
	v_mul_f32_e32 v45, v43, v43
	v_mul_f32_e32 v51, v47, v47
	v_fmac_f32_e32 v44, v40, v40
	v_fmac_f32_e32 v45, v42, v42
	s_waitcnt vmcnt(3)
	v_pk_add_f32 v[38:39], v[38:39], v[70:71]
	v_pk_add_f32 v[36:37], v[36:37], v[68:69]
	v_fmac_f32_e32 v51, v46, v46
	v_add_f32_e32 v44, v44, v45
	v_cvt_pk_bf16_f32 v40, v40, v41
	v_mul_f32_e32 v41, v37, v37
	v_mul_f32_e32 v45, v39, v39
	v_add_f32_e32 v50, v50, v51
	v_fmac_f32_e32 v41, v36, v36
	v_fmac_f32_e32 v45, v38, v38
	v_add_f32_e32 v44, v50, v44
	v_add_f32_e32 v41, v41, v45
	v_add_f32_e32 v41, v44, v41
	s_waitcnt vmcnt(2)
	v_pk_add_f32 v[34:35], v[34:35], v[66:67]
	v_pk_add_f32 v[44:45], v[32:33], v[64:65]
	v_mul_f32_e32 v33, v35, v35
	v_mul_f32_e32 v32, v45, v45
	v_fmac_f32_e32 v32, v44, v44
	v_fmac_f32_e32 v33, v34, v34
	v_add_f32_e32 v32, v32, v33
	v_add_f32_e32 v32, v41, v32
	ds_bpermute_b32 v33, v119, v32
	v_cvt_pk_bf16_f32 v41, v42, v43
	v_mov_b32_e32 v198, v40
	v_mov_b32_e32 v199, v41
	v_bfe_u32 v194, v252, 4, 1
	v_mul_u32_u24_e32 v194, 24, v194
	v_mov_b32_e32 v195, 0
	v_lshl_add_u64 v[200:201], v[48:49], 0, v[194:195]
	v_permlane16_swap_b32_e32 v196, v198
	v_permlane16_swap_b32_e32 v197, v199
	global_store_dwordx4 v[200:201], v[196:199], off
	s_nop 1
	v_cvt_pk_bf16_f32 v36, v36, v37
	v_cvt_pk_bf16_f32 v37, v38, v39
	s_waitcnt lgkmcnt(0)
	v_add_f32_e32 v32, v32, v33
	ds_bpermute_b32 v33, v120, v32
	v_mov_b32_e32 v196, v36
	v_mov_b32_e32 v197, v37
	v_cvt_pk_bf16_f32 v36, v44, v45
	v_cvt_pk_bf16_f32 v37, v34, v35
	v_mov_b32_e32 v198, v36
	v_mov_b32_e32 v199, v37
	v_bfe_u32 v194, v252, 4, 1
	v_mul_u32_u24_e32 v194, 24, v194
	v_mov_b32_e32 v195, 0
	v_lshl_add_u64 v[200:201], v[48:49], 0, v[194:195]
	v_permlane16_swap_b32_e32 v196, v198
	v_permlane16_swap_b32_e32 v197, v199
	global_store_dwordx4 v[200:201], v[196:199], off offset:256
	s_nop 1
	s_and_saveexec_b64 s[0:1], vcc
	s_cbranch_execz .LBB0_617
	s_waitcnt lgkmcnt(0)
	v_add_f32_e32 v32, v32, v33
	ds_write_b32 v118, v32 offset:576
; __device__ __forceinline__ u32x2 pack4(float a, float b, float c, float d) { return u32x2{cvtpk(a, b), cvtpk(c, d)}; }
; __device__ __forceinline__ u32x2 pack4(const f32x4& v) { return u32x2{cvtpk(v[0], v[1]), cvtpk(v[2], v[3])}; }
; #define SBAR() __builtin_amdgcn_sched_barrier(0)
; __global__ void __launch_bounds__(512) fwd_megakernel(Params p) {
;     ...
;         for (int ai = 0; ai < 2; ++ai)
;           #pragma unroll
;           for (int mp = 0; mp < 2; ++mp) { SBAR();
;             f32x4 xv[2][2][2];
;             #pragma unroll
;             for (int mm = 0; mm < 2; ++mm) {
;               const float* xr = xrow_ptr(p, brow + ai * 128 + wr * 64 + (mp * 2 + mm) * 16 + fr) + pn * 256 + wc * 32 + fq * 4;
;               #pragma unroll
;               for (int bj = 0; bj < 2; ++bj)
;                 #pragma unroll
;                 for (int n = 0; n < 2; ++n) xv[mm][bj][n] = *reinterpret_cast<const f32x4*>(xr + bj * 128 + n * 16);
;             }
;             SBAR();
;             #pragma unroll
;             for (int mm = 0; mm < 2; ++mm) {
;               const int m = mp * 2 + mm;
;               int lrow = ai * 128 + wr * 64 + m * 16 + fr, row = brow + lrow; float ss = 0.f;
;               bf16* hd = p_h1b + (long)row * DM + pn * 256 + wc * 32 + fq * 4;
;               #pragma unroll
;               for (int bj = 0; bj < 2; ++bj)
;                 #pragma unroll
;                 for (int n = 0; n < 2; ++n) {
;                   f32x4 v = acc[ai][bj][m][n] + xv[mm][bj][n];
;                   ss += (v[0] * v[0] + v[1] * v[1]) + (v[2] * v[2] + v[3] * v[3]);
;                   *reinterpret_cast<u32x2*>(hd + bj * 128 + n * 16) = pack4(v);
;                 }
;               ss += __shfl_xor(ss, 16); ss += __shfl_xor(ss, 32);
;               if (fq == 0) red[wc * 256 + lrow] = ss;
;             }
.LBB0_617:
	s_or_b64 exec, exec, s[0:1]
	v_add_u32_e32 v66, 0xa0, v148
	v_add_u32_e32 v32, 0xffff80a0, v148
	v_ashrrev_i32_e32 v67, 31, v66
	v_cmp_gt_i32_e64 s[0:1], s60, v66
	v_mov_b32_e32 v36, s39
	v_mov_b32_e32 v37, s37
	s_waitcnt lgkmcnt(0)
	v_cndmask_b32_e64 v33, 0, v67, s[0:1]
	v_cndmask_b32_e64 v32, v32, v66, s[0:1]
	v_mov_b32_e32 v38, s38
	v_mov_b32_e32 v39, s36
	v_cndmask_b32_e64 v35, v36, v37, s[0:1]
	v_cndmask_b32_e64 v34, v38, v39, s[0:1]
	v_lshlrev_b64 v[32:33], 12, v[32:33]
	v_lshl_add_u64 v[32:33], v[34:35], 0, v[32:33]
	v_lshl_add_u64 v[32:33], v[32:33], 0, s[44:45]
	v_mov_b32_e32 v115, v147
	v_lshl_add_u64 v[32:33], v[32:33], 0, v[114:115]
	v_mov_b32_e32 v117, v147
	v_lshl_add_u64 v[32:33], v[32:33], 0, v[116:117]
	v_add_u32_e32 v48, 0xb0, v148
	global_load_dwordx4 v[50:53], v[32:33], off
	global_load_dwordx4 v[54:57], v[32:33], off offset:64
	global_load_dwordx4 v[58:61], v[32:33], off offset:512
	global_load_dwordx4 v[62:65], v[32:33], off offset:576
	v_add_u32_e32 v32, 0xffff80b0, v148
	v_ashrrev_i32_e32 v49, 31, v48
	v_cmp_gt_i32_e64 s[0:1], s60, v48
	s_nop 1
	v_cndmask_b32_e64 v33, 0, v49, s[0:1]
	v_cndmask_b32_e64 v32, v32, v48, s[0:1]
	v_cndmask_b32_e64 v35, v36, v37, s[0:1]
	v_cndmask_b32_e64 v34, v38, v39, s[0:1]
	v_lshlrev_b64 v[32:33], 12, v[32:33]
	v_lshl_add_u64 v[32:33], v[34:35], 0, v[32:33]
	v_lshl_add_u64 v[32:33], v[32:33], 0, s[44:45]
	v_lshl_add_u64 v[32:33], v[32:33], 0, v[114:115]
	v_lshl_add_u64 v[32:33], v[32:33], 0, v[116:117]
	global_load_dwordx4 v[44:47], v[32:33], off
	global_load_dwordx4 v[40:43], v[32:33], off offset:64
	global_load_dwordx4 v[36:39], v[32:33], off offset:512
	s_nop 0
	global_load_dwordx4 v[32:35], v[32:33], off offset:576
	v_lshlrev_b64 v[66:67], 11, v[66:67]
	v_lshl_add_u64 v[66:67], s[26:27], 0, v[66:67]
	v_lshl_add_u64 v[66:67], s[42:43], 1, v[66:67]
	s_waitcnt vmcnt(7)
	v_pk_add_f32 v[28:29], v[28:29], v[50:51]
	v_lshl_add_u64 v[66:67], v[66:67], 0, v[146:147]
	v_mul_f32_e32 v50, v29, v29
	v_lshl_add_u64 v[66:67], v[66:67], 0, v[112:113]
	v_pk_add_f32 v[30:31], v[30:31], v[52:53]
	v_fmac_f32_e32 v50, v28, v28
	v_cvt_pk_bf16_f32 v28, v28, v29
	v_cvt_pk_bf16_f32 v29, v30, v31
	s_waitcnt vmcnt(6)
	v_pk_add_f32 v[26:27], v[26:27], v[56:57]
	v_pk_add_f32 v[24:25], v[24:25], v[54:55]
	v_mov_b32_e32 v196, v28
	v_mov_b32_e32 v197, v29
	v_mul_f32_e32 v28, v25, v25
	v_mul_f32_e32 v29, v27, v27
	v_mul_f32_e32 v51, v31, v31
	v_fmac_f32_e32 v28, v24, v24
	v_fmac_f32_e32 v29, v26, v26
	s_waitcnt vmcnt(5)
	v_pk_add_f32 v[22:23], v[22:23], v[60:61]
	v_pk_add_f32 v[20:21], v[20:21], v[58:59]
	v_fmac_f32_e32 v51, v30, v30
	v_add_f32_e32 v28, v28, v29
	v_cvt_pk_bf16_f32 v24, v24, v25
	v_mul_f32_e32 v25, v21, v21
	v_mul_f32_e32 v29, v23, v23
	v_add_f32_e32 v50, v50, v51
	v_fmac_f32_e32 v25, v20, v20
	v_fmac_f32_e32 v29, v22, v22
	v_add_f32_e32 v28, v50, v28
	v_add_f32_e32 v25, v25, v29
	v_add_f32_e32 v25, v28, v25
	s_waitcnt vmcnt(4)
	v_pk_add_f32 v[18:19], v[18:19], v[64:65]
	v_pk_add_f32 v[28:29], v[16:17], v[62:63]
	v_mul_f32_e32 v17, v19, v19
	v_mul_f32_e32 v16, v29, v29
	v_fmac_f32_e32 v16, v28, v28
	v_fmac_f32_e32 v17, v18, v18
	v_add_f32_e32 v16, v16, v17
	v_add_f32_e32 v16, v25, v16
	ds_bpermute_b32 v17, v119, v16
	v_cvt_pk_bf16_f32 v25, v26, v27
	v_mov_b32_e32 v198, v24
	v_mov_b32_e32 v199, v25
	v_bfe_u32 v194, v252, 4, 1
	v_mul_u32_u24_e32 v194, 24, v194
	v_mov_b32_e32 v195, 0
	v_lshl_add_u64 v[200:201], v[66:67], 0, v[194:195]
	v_permlane16_swap_b32_e32 v196, v198
	v_permlane16_swap_b32_e32 v197, v199
	global_store_dwordx4 v[200:201], v[196:199], off
	s_nop 1
	v_cvt_pk_bf16_f32 v20, v20, v21
	v_cvt_pk_bf16_f32 v21, v22, v23
	s_waitcnt lgkmcnt(0)
	v_add_f32_e32 v16, v16, v17
	ds_bpermute_b32 v17, v120, v16
	v_mov_b32_e32 v196, v20
	v_mov_b32_e32 v197, v21
	v_cvt_pk_bf16_f32 v20, v28, v29
	v_cvt_pk_bf16_f32 v21, v18, v19
	v_mov_b32_e32 v198, v20
	v_mov_b32_e32 v199, v21
	v_bfe_u32 v194, v252, 4, 1
	v_mul_u32_u24_e32 v194, 24, v194
	v_mov_b32_e32 v195, 0
	v_lshl_add_u64 v[200:201], v[66:67], 0, v[194:195]
	v_permlane16_swap_b32_e32 v196, v198
	v_permlane16_swap_b32_e32 v197, v199
	global_store_dwordx4 v[200:201], v[196:199], off offset:256
	s_nop 1
	s_and_saveexec_b64 s[0:1], vcc
	s_cbranch_execz .LBB0_619
	s_waitcnt lgkmcnt(0)
	v_add_f32_e32 v16, v16, v17
	ds_write_b32 v118, v16 offset:640
.LBB0_619:
	s_or_b64 exec, exec, s[0:1]
	s_waitcnt lgkmcnt(0)
	v_lshlrev_b64 v[16:17], 11, v[48:49]
	v_lshl_add_u64 v[16:17], s[26:27], 0, v[16:17]
	v_lshl_add_u64 v[16:17], s[42:43], 1, v[16:17]
	s_waitcnt vmcnt(5)
	v_pk_add_f32 v[12:13], v[12:13], v[44:45]
	v_lshl_add_u64 v[16:17], v[16:17], 0, v[146:147]
	v_mov_b32_e32 v113, v147
	v_mul_f32_e32 v18, v13, v13
	v_lshl_add_u64 v[16:17], v[16:17], 0, v[112:113]
	v_pk_add_f32 v[14:15], v[14:15], v[46:47]
	v_fmac_f32_e32 v18, v12, v12
	v_cvt_pk_bf16_f32 v12, v12, v13
	v_cvt_pk_bf16_f32 v13, v14, v15
	s_waitcnt vmcnt(4)
	v_pk_add_f32 v[10:11], v[10:11], v[42:43]
	v_pk_add_f32 v[8:9], v[8:9], v[40:41]
	v_mov_b32_e32 v196, v12
	v_mov_b32_e32 v197, v13
	v_mul_f32_e32 v12, v9, v9
	v_mul_f32_e32 v13, v11, v11
	v_mul_f32_e32 v19, v15, v15
	v_fmac_f32_e32 v12, v8, v8
	v_fmac_f32_e32 v13, v10, v10
	s_waitcnt vmcnt(3)
	v_pk_add_f32 v[6:7], v[6:7], v[38:39]
	v_pk_add_f32 v[4:5], v[4:5], v[36:37]
	v_fmac_f32_e32 v19, v14, v14
	v_add_f32_e32 v12, v12, v13
	v_cvt_pk_bf16_f32 v8, v8, v9
	v_mul_f32_e32 v9, v5, v5
	v_mul_f32_e32 v13, v7, v7
	v_add_f32_e32 v18, v18, v19
	v_fmac_f32_e32 v9, v4, v4
	v_fmac_f32_e32 v13, v6, v6
	v_add_f32_e32 v12, v18, v12
	v_add_f32_e32 v9, v9, v13
	v_add_f32_e32 v9, v12, v9
	s_waitcnt vmcnt(2)
	v_pk_add_f32 v[2:3], v[2:3], v[34:35]
	v_pk_add_f32 v[12:13], v[0:1], v[32:33]
	v_mul_f32_e32 v1, v3, v3
	v_mul_f32_e32 v0, v13, v13
	v_fmac_f32_e32 v0, v12, v12
	v_fmac_f32_e32 v1, v2, v2
	v_add_f32_e32 v0, v0, v1
	v_add_f32_e32 v0, v9, v0
	ds_bpermute_b32 v1, v119, v0
	v_cvt_pk_bf16_f32 v9, v10, v11
	v_mov_b32_e32 v198, v8
	v_mov_b32_e32 v199, v9
	v_bfe_u32 v194, v252, 4, 1
	v_mul_u32_u24_e32 v194, 24, v194
	v_mov_b32_e32 v195, 0
	v_lshl_add_u64 v[200:201], v[16:17], 0, v[194:195]
	v_permlane16_swap_b32_e32 v196, v198
	v_permlane16_swap_b32_e32 v197, v199
	global_store_dwordx4 v[200:201], v[196:199], off
	s_nop 1
	v_cvt_pk_bf16_f32 v4, v4, v5
	v_cvt_pk_bf16_f32 v5, v6, v7
	s_waitcnt lgkmcnt(0)
	v_add_f32_e32 v0, v0, v1
	ds_bpermute_b32 v1, v120, v0
	v_mov_b32_e32 v196, v4
	v_mov_b32_e32 v197, v5
	v_cvt_pk_bf16_f32 v4, v12, v13
	v_cvt_pk_bf16_f32 v5, v2, v3
	v_mov_b32_e32 v198, v4
	v_mov_b32_e32 v199, v5
	v_bfe_u32 v194, v252, 4, 1
	v_mul_u32_u24_e32 v194, 24, v194
	v_mov_b32_e32 v195, 0
	v_lshl_add_u64 v[200:201], v[16:17], 0, v[194:195]
	v_permlane16_swap_b32_e32 v196, v198
	v_permlane16_swap_b32_e32 v197, v199
	global_store_dwordx4 v[200:201], v[196:199], off offset:256
	s_nop 1
	s_and_saveexec_b64 s[0:1], vcc
	s_cbranch_execz .LBB0_621
	s_waitcnt lgkmcnt(0)
	v_add_f32_e32 v0, v0, v1
	ds_write_b32 v118, v0 offset:704

;   #define WAIT_V(n) asm volatile("s_waitcnt vmcnt(" #n ")":::"memory")
;   #define BAR __builtin_amdgcn_s_barrier()
; template <class Pre, class Fin, class Epi> ...
;     ...
;   if (pf && pfE == 16)      { WAIT_V(26); BAR; WAIT_V(22); BAR; }
.LBB0_676:
	s_waitcnt vmcnt(18)
	s_barrier
	s_waitcnt vmcnt(14)
	s_barrier

;   #define STAGEA(P,br,kt) STAGE(P,A,lda,br,kt,oa0,oa1)
;   #define LDA(dst,b,h) _Pragma("unroll") for(int m=0;m<4;++m) _Pragma("unroll") for(int k=0;k<2;++k) \
;     dst[m][k]=*reinterpret_cast<const bf16x8*>((char*)SA(b,h)+lds_byte(wr*64+m*16+fr,k*32+fq*8))
;   #define LDB(dst,b,h) _Pragma("unroll") for(int n=0;n<2;++n) _Pragma("unroll") for(int k=0;k<2;++k) \
;     dst[n][k]=*reinterpret_cast<const bf16x8*>((char*)SB(b,h)+lds_byte(wc*32+n*16+fr,k*32+fq*8))
;   #define WAIT_V(n) asm volatile("s_waitcnt vmcnt(" #n ")":::"memory")
;   #define BAR __builtin_amdgcn_s_barrier()
;   #define SCHED __builtin_amdgcn_sched_barrier(0)
; template <class Pre, class Fin, class Epi> ...
;     ...
;   if(wr==1)BAR;
;   if (pf && pfE == 16)      { WAIT_V(26); BAR; WAIT_V(22); BAR; }
;   else if (pf && pfE == 32) { WAIT_V(42); BAR; WAIT_V(38); BAR; }
;   else                      { WAIT_V(10); BAR; WAIT_V(6); BAR; }
;   for(int t=0;t<nt-2;t+=2){
;     LDB(B0,0,0); SCHED; LDA(At,0,0); STAGEA(SA(1,1),brow+HALF,t+1);
.LBB0_737:
	s_andn2_b64 vcc, exec, s[38:39]
	s_cbranch_vccnz .LBB0_739
.LBB0_738:
	s_waitcnt vmcnt(26)
	s_barrier
	s_waitcnt vmcnt(22)
	s_barrier
.LBB0_739:
	v_and_b32_e32 v2, 15, v142
	v_lshlrev_b32_e32 v1, 6, v142
	v_and_b32_e32 v149, 0x3000, v1
	v_lshlrev_b32_e32 v1, 6, v2
	v_lshlrev_b32_e32 v2, 2, v2
	v_and_b32_e32 v0, 48, v142
	s_cmpk_gt_i32 s42, 0xbf
	s_mov_b64 s[40:41], -1
	v_or_b32_e32 v154, 0x400, v149
	v_or_b32_e32 v152, 0x800, v149
	v_or_b32_e32 v153, 0xc00, v149
	v_lshlrev_b32_e32 v166, 13, v3
	v_and_b32_e32 v2, 32, v2
	s_cbranch_scc1 .LBB0_741
	v_lshlrev_b32_e32 v167, 13, v3
	s_or_b32 s36, s29, 0x80
	v_or_b32_e32 v131, 0x400, v149
	v_or_b32_e32 v133, 0x800, v149
	v_or_b32_e32 v135, 0xc00, v149
	v_bitop3_b32 v155, v1, v2, v0 bitop3:0x36
	v_or_b32_e32 v157, 0x400, v167
	v_or_b32_e32 v158, 0x800, v167
	v_or_b32_e32 v159, 0xc00, v167
	v_or_b32_e32 v161, 0x1000, v167
	v_or_b32_e32 v162, 0x1400, v167
	v_or_b32_e32 v163, 0x1800, v167
	v_or_b32_e32 v164, 0x1c00, v167
	s_mul_hi_i32 s37, s36, 0x1600
	s_mulk_i32 s36, 0x1600
	s_mov_b64 s[40:41], 0

; __device__ __forceinline__ u32x2 pack4(float a, float b, float c, float d) { return u32x2{cvtpk(a, b), cvtpk(c, d)}; }
; __device__ __forceinline__ u32x2 pack4(const f32x4& v) { return u32x2{cvtpk(v[0], v[1]), cvtpk(v[2], v[3])}; }
; #define SBAR() __builtin_amdgcn_sched_barrier(0)
; __global__ void __launch_bounds__(512) fwd_megakernel(Params p) {
;     ...
;         float* red = (float*)(shm_raw + EPI_LDS_OFF);
;         #pragma unroll
;         for (int ai = 0; ai < 2; ++ai) { SBAR();
;           u32x2 hv[4][2][2];
;           #pragma unroll
;           for (int m = 0; m < 4; ++m) {
;             const bf16* hr = p_h1b + (long)(brow + ai * 128 + wr * 64 + m * 16 + fr) * DM + pn * 256 + wc * 32 + fq * 4;
;             #pragma unroll
;             for (int bj = 0; bj < 2; ++bj)
;               #pragma unroll
;               for (int n = 0; n < 2; ++n) hv[m][bj][n] = *reinterpret_cast<const u32x2*>(hr + bj * 128 + n * 16);
;           }
;           SBAR();
;           #pragma unroll
;           for (int m = 0; m < 4; ++m) {
;             int lrow = ai * 128 + wr * 64 + m * 16 + fr, row = brow + lrow; float ss = 0.f;
;             bf16* od = p_h2b + (long)row * DM + pn * 256 + wc * 32 + fq * 4;
;             #pragma unroll
;             for (int bj = 0; bj < 2; ++bj)
;               #pragma unroll
;               for (int n = 0; n < 2; ++n) {
;                 const u32x2 hw = hv[m][bj][n];
;                 f32x4 v = acc[ai][bj][m][n];
;                 v[0] += __uint_as_float(hw[0] << 16); v[1] += __uint_as_float(hw[0] & 0xffff0000u);
;                 v[2] += __uint_as_float(hw[1] << 16); v[3] += __uint_as_float(hw[1] & 0xffff0000u);
;                 ss += (v[0] * v[0] + v[1] * v[1]) + (v[2] * v[2] + v[3] * v[3]);
;                 *reinterpret_cast<u32x2*>(od + bj * 128 + n * 16) = pack4(v);
;               }
;             ss += __shfl_xor(ss, 16); ss += __shfl_xor(ss, 32);
;             if (fq == 0) red[wc * 256 + lrow] = ss;
;           }
.LBB0_749:
	v_mov_b32_e32 v128, v252
	s_waitcnt lgkmcnt(0)
	s_barrier
	s_nop 0
	v_bfe_u32 v162, v128, 6, 2
	v_and_b32_e32 v130, 15, v128
	v_bfe_u32 v163, v128, 4, 2
	v_ashrrev_i32_e32 v128, 2, v128
	v_and_or_b32 v161, v128, s51, v130
	v_cmp_eq_u32_e32 vcc, 0, v163
	v_lshl_add_u32 v176, v162, 10, s69
	s_ashr_i32 s31, s30, 31
	s_lshl_b64 s[0:1], s[30:31], 1
	s_add_u32 s36, s26, s0
	v_add_u32_e32 v130, s29, v161
	s_addc_u32 s37, s27, s1
	v_lshlrev_b32_e32 v128, 6, v162
	v_lshl_add_u64 v[132:133], s[36:37], 0, v[128:129]
	v_lshlrev_b32_e32 v164, 3, v163
	v_mov_b32_e32 v165, v129
	v_ashrrev_i32_e32 v131, 31, v130
	v_lshl_add_u64 v[132:133], v[132:133], 0, v[164:165]
	v_lshlrev_b64 v[166:167], 11, v[130:131]
	v_lshl_add_u64 v[134:135], v[132:133], 0, v[166:167]
	global_load_dwordx2 v[168:169], v[134:135], off
	global_load_dwordx2 v[170:171], v[134:135], off offset:32
	global_load_dwordx2 v[172:173], v[134:135], off offset:256
	global_load_dwordx2 v[174:175], v[134:135], off offset:288
	v_or_b32_e32 v134, 16, v130
	v_ashrrev_i32_e32 v135, 31, v134
	v_lshlrev_b64 v[134:135], 11, v[134:135]
	v_lshl_add_u64 v[134:135], v[132:133], 0, v[134:135]
	global_load_dwordx2 v[158:159], v[134:135], off
	global_load_dwordx2 v[156:157], v[134:135], off offset:32
	global_load_dwordx2 v[154:155], v[134:135], off offset:256
	global_load_dwordx2 v[152:153], v[134:135], off offset:288
	v_or_b32_e32 v134, 32, v130
	v_ashrrev_i32_e32 v135, 31, v134
	v_lshlrev_b64 v[134:135], 11, v[134:135]
	v_lshl_add_u64 v[134:135], v[132:133], 0, v[134:135]
	global_load_dwordx2 v[150:151], v[134:135], off
	global_load_dwordx2 v[148:149], v[134:135], off offset:32
	global_load_dwordx2 v[146:147], v[134:135], off offset:256
	global_load_dwordx2 v[142:143], v[134:135], off offset:288
	v_or_b32_e32 v134, 48, v130
	v_ashrrev_i32_e32 v135, 31, v134
	v_lshlrev_b64 v[134:135], 11, v[134:135]
	v_lshl_add_u64 v[134:135], v[132:133], 0, v[134:135]
	global_load_dwordx2 v[140:141], v[134:135], off
	global_load_dwordx2 v[138:139], v[134:135], off offset:32
	global_load_dwordx2 v[136:137], v[134:135], off offset:256
	s_nop 0
	global_load_dwordx2 v[134:135], v[134:135], off offset:288
	v_lshl_add_u64 v[166:167], s[26:27], 0, v[166:167]
	v_lshl_add_u64 v[166:167], v[166:167], 0, s[0:1]
	v_lshl_add_u64 v[166:167], v[166:167], 0, v[128:129]
	s_waitcnt vmcnt(0)
	v_lshlrev_b32_e32 v128, 16, v168
	v_add_f32_e32 v124, v124, v128
	v_and_b32_e32 v128, 0xffff0000, v168
	v_add_f32_e32 v125, v125, v128
	v_lshlrev_b32_e32 v128, 16, v169
	v_add_f32_e32 v126, v126, v128
	v_and_b32_e32 v128, 0xffff0000, v169
	v_add_f32_e32 v127, v127, v128
	v_mul_f32_e32 v128, v125, v125
	v_lshl_add_u64 v[164:165], v[166:167], 0, v[164:165]
	v_fmac_f32_e32 v128, v124, v124
	v_cvt_pk_bf16_f32 v124, v124, v125
	v_cvt_pk_bf16_f32 v125, v126, v127
	v_mov_b32_e32 v200, v124
	v_mov_b32_e32 v201, v125
	v_lshlrev_b32_e32 v124, 16, v170
	v_add_f32_e32 v116, v116, v124
	v_and_b32_e32 v124, 0xffff0000, v170
	v_add_f32_e32 v117, v117, v124
	v_lshlrev_b32_e32 v124, 16, v171
	v_add_f32_e32 v118, v118, v124
	v_and_b32_e32 v124, 0xffff0000, v171
	v_add_f32_e32 v119, v119, v124
	v_mul_f32_e32 v124, v117, v117
	v_fmac_f32_e32 v124, v116, v116
	v_mul_f32_e32 v125, v119, v119
	v_cvt_pk_bf16_f32 v116, v116, v117
	v_cvt_pk_bf16_f32 v117, v118, v119
	v_and_b32_e32 v119, 0xffff0000, v172
	v_fmac_f32_e32 v125, v118, v118
	v_lshlrev_b32_e32 v118, 16, v172
	v_add_f32_e32 v119, v121, v119
	v_and_b32_e32 v121, 0xffff0000, v173
	v_add_f32_e32 v118, v120, v118
	v_lshlrev_b32_e32 v120, 16, v173
	v_add_f32_e32 v121, v123, v121
	v_mul_f32_e32 v131, v127, v127
	v_add_f32_e32 v120, v122, v120
	v_mul_f32_e32 v122, v119, v119
	v_mul_f32_e32 v123, v121, v121
	v_fmac_f32_e32 v131, v126, v126
	v_fmac_f32_e32 v122, v118, v118
	v_fmac_f32_e32 v123, v120, v120
	v_add_f32_e32 v128, v128, v131
	v_add_f32_e32 v124, v124, v125
	v_add_f32_e32 v122, v122, v123
	v_lshlrev_b32_e32 v123, 16, v174
	v_add_f32_e32 v124, v128, v124
	v_add_f32_e32 v123, v112, v123
	v_and_b32_e32 v112, 0xffff0000, v174
	v_add_f32_e32 v122, v124, v122
	v_add_f32_e32 v124, v113, v112
	v_lshlrev_b32_e32 v112, 16, v175
	v_add_f32_e32 v114, v114, v112
	v_and_b32_e32 v112, 0xffff0000, v175
	v_add_f32_e32 v125, v115, v112
	v_mul_f32_e32 v112, v124, v124
	v_mul_f32_e32 v113, v125, v125
	v_fmac_f32_e32 v112, v123, v123
	v_fmac_f32_e32 v113, v114, v114
	v_add_f32_e32 v112, v112, v113
	v_and_b32_e32 v113, 64, v145
	v_add_f32_e32 v122, v122, v112
	v_xor_b32_e32 v112, 16, v145
	v_add_u32_e32 v126, 64, v113
	v_cmp_lt_i32_e64 s[0:1], v112, v126
	v_mov_b32_e32 v202, v116
	v_mov_b32_e32 v203, v117
	v_bfe_u32 v206, v252, 4, 1
	v_mul_u32_u24_e32 v206, 24, v206
	v_mov_b32_e32 v207, 0
	v_lshl_add_u64 v[204:205], v[164:165], 0, v[206:207]
	v_permlane16_swap_b32_e32 v200, v202
	v_permlane16_swap_b32_e32 v201, v203
	global_store_dwordx4 v[204:205], v[200:203], off
	s_nop 1
	s_nop 0
	v_cndmask_b32_e64 v112, v145, v112, s[0:1]
	v_lshlrev_b32_e32 v115, 2, v112
	ds_bpermute_b32 v127, v115, v122
	v_cvt_pk_bf16_f32 v112, v118, v119
	v_cvt_pk_bf16_f32 v113, v120, v121
	v_mov_b32_e32 v200, v112
	v_mov_b32_e32 v201, v113
	v_xor_b32_e32 v113, 32, v145
	v_cmp_lt_i32_e64 s[0:1], v113, v126
	s_waitcnt lgkmcnt(0)
	v_add_f32_e32 v112, v122, v127
	v_cvt_pk_bf16_f32 v118, v123, v124
	v_cvt_pk_bf16_f32 v119, v114, v125
	v_lshl_add_u32 v114, v161, 2, v176
	v_cndmask_b32_e64 v113, v145, v113, s[0:1]
	v_lshlrev_b32_e32 v116, 2, v113
	ds_bpermute_b32 v113, v116, v112
	v_mov_b32_e32 v202, v118
	v_mov_b32_e32 v203, v119
	v_bfe_u32 v206, v252, 4, 1
	v_mul_u32_u24_e32 v206, 24, v206
	v_mov_b32_e32 v207, 0
	v_lshl_add_u64 v[204:205], v[164:165], 0, v[206:207]
	v_permlane16_swap_b32_e32 v200, v202
	v_permlane16_swap_b32_e32 v201, v203
	global_store_dwordx4 v[204:205], v[200:203], off offset:256
	s_nop 1
	s_and_saveexec_b64 s[0:1], vcc
	s_cbranch_execz .LBB0_751
	s_waitcnt lgkmcnt(0)
	v_add_f32_e32 v112, v112, v113
	ds_write_b32 v114, v112
; __device__ __forceinline__ u32x2 pack4(float a, float b, float c, float d) { return u32x2{cvtpk(a, b), cvtpk(c, d)}; }
; __device__ __forceinline__ u32x2 pack4(const f32x4& v) { return u32x2{cvtpk(v[0], v[1]), cvtpk(v[2], v[3])}; }
; __global__ void __launch_bounds__(512) fwd_megakernel(Params p) {
;     ...
;           #pragma unroll
;           for (int m = 0; m < 4; ++m) {
;             int lrow = ai * 128 + wr * 64 + m * 16 + fr, row = brow + lrow; float ss = 0.f;
;             bf16* od = p_h2b + (long)row * DM + pn * 256 + wc * 32 + fq * 4;
;             #pragma unroll
;             for (int bj = 0; bj < 2; ++bj)
;               #pragma unroll
;               for (int n = 0; n < 2; ++n) {
;                 const u32x2 hw = hv[m][bj][n];
;                 f32x4 v = acc[ai][bj][m][n];
;                 v[0] += __uint_as_float(hw[0] << 16); v[1] += __uint_as_float(hw[0] & 0xffff0000u);
;                 v[2] += __uint_as_float(hw[1] << 16); v[3] += __uint_as_float(hw[1] & 0xffff0000u);
;                 ss += (v[0] * v[0] + v[1] * v[1]) + (v[2] * v[2] + v[3] * v[3]);
;                 *reinterpret_cast<u32x2*>(od + bj * 128 + n * 16) = pack4(v);
;               }
;             ss += __shfl_xor(ss, 16); ss += __shfl_xor(ss, 32);
;             if (fq == 0) red[wc * 256 + lrow] = ss;
;           }
.LBB0_751:
	s_or_b64 exec, exec, s[0:1]
	v_lshlrev_b32_e32 v117, 5, v162
	v_add3_u32 v112, s29, v161, 16
	s_waitcnt lgkmcnt(0)
	v_ashrrev_i32_e32 v113, 31, v112
	v_lshlrev_b32_e32 v128, 1, v117
	v_lshlrev_b32_e32 v117, 16, v158
	v_lshlrev_b64 v[112:113], 11, v[112:113]
	v_add_f32_e32 v108, v108, v117
	v_and_b32_e32 v117, 0xffff0000, v158
	v_lshl_add_u64 v[112:113], s[26:27], 0, v[112:113]
	v_add_f32_e32 v109, v109, v117
	v_lshlrev_b32_e32 v117, 16, v159
	v_lshlrev_b32_e32 v120, 2, v163
	v_lshl_add_u64 v[112:113], s[30:31], 1, v[112:113]
	v_add_f32_e32 v110, v110, v117
	v_and_b32_e32 v117, 0xffff0000, v159
	v_lshl_add_u64 v[118:119], v[112:113], 0, v[128:129]
	v_lshlrev_b32_e32 v112, 1, v120
	v_mov_b32_e32 v113, v129
	v_add_f32_e32 v111, v111, v117
	v_mul_f32_e32 v117, v109, v109
	v_lshl_add_u64 v[118:119], v[118:119], 0, v[112:113]
	v_fmac_f32_e32 v117, v108, v108
	v_cvt_pk_bf16_f32 v108, v108, v109
	v_cvt_pk_bf16_f32 v109, v110, v111
	v_mov_b32_e32 v200, v108
	v_mov_b32_e32 v201, v109
	v_lshlrev_b32_e32 v108, 16, v156
	v_add_f32_e32 v100, v100, v108
	v_and_b32_e32 v108, 0xffff0000, v156
	v_add_f32_e32 v101, v101, v108
	v_lshlrev_b32_e32 v108, 16, v157
	v_add_f32_e32 v102, v102, v108
	v_and_b32_e32 v108, 0xffff0000, v157
	v_add_f32_e32 v103, v103, v108
	v_mul_f32_e32 v108, v101, v101
	v_fmac_f32_e32 v108, v100, v100
	v_cvt_pk_bf16_f32 v100, v100, v101
	v_lshlrev_b32_e32 v101, 16, v154
	v_add_f32_e32 v104, v104, v101
	v_and_b32_e32 v101, 0xffff0000, v154
	v_add_f32_e32 v105, v105, v101
	v_lshlrev_b32_e32 v101, 16, v155
	v_mul_f32_e32 v109, v103, v103
	v_add_f32_e32 v106, v106, v101
	v_and_b32_e32 v101, 0xffff0000, v155
	v_mul_f32_e32 v120, v111, v111
	v_fmac_f32_e32 v109, v102, v102
	v_add_f32_e32 v107, v107, v101
	v_fmac_f32_e32 v120, v110, v110
	v_add_f32_e32 v108, v108, v109
	v_mul_f32_e32 v101, v105, v105
	v_mul_f32_e32 v109, v107, v107
	v_add_f32_e32 v117, v117, v120
	v_fmac_f32_e32 v101, v104, v104
	v_fmac_f32_e32 v109, v106, v106
	v_add_f32_e32 v108, v117, v108
	v_add_f32_e32 v101, v101, v109
	v_add_f32_e32 v101, v108, v101
	v_lshlrev_b32_e32 v108, 16, v152
	v_add_f32_e32 v108, v96, v108
	v_and_b32_e32 v96, 0xffff0000, v152
	v_add_f32_e32 v109, v97, v96
	v_lshlrev_b32_e32 v96, 16, v153
	v_add_f32_e32 v110, v98, v96
	v_and_b32_e32 v96, 0xffff0000, v153
	v_add_f32_e32 v111, v99, v96
	v_mul_f32_e32 v96, v109, v109
	v_mul_f32_e32 v97, v111, v111
	v_fmac_f32_e32 v96, v108, v108
	v_fmac_f32_e32 v97, v110, v110
	v_add_f32_e32 v96, v96, v97
	v_add_f32_e32 v96, v101, v96
	ds_bpermute_b32 v97, v115, v96
	v_cvt_pk_bf16_f32 v101, v102, v103
	v_mov_b32_e32 v202, v100
	v_mov_b32_e32 v203, v101
	v_bfe_u32 v206, v252, 4, 1
	v_mul_u32_u24_e32 v206, 24, v206
	v_mov_b32_e32 v207, 0
	v_lshl_add_u64 v[204:205], v[118:119], 0, v[206:207]
	v_permlane16_swap_b32_e32 v200, v202
	v_permlane16_swap_b32_e32 v201, v203
	global_store_dwordx4 v[204:205], v[200:203], off
	s_nop 1
	v_cvt_pk_bf16_f32 v98, v104, v105
	v_cvt_pk_bf16_f32 v99, v106, v107
	s_waitcnt lgkmcnt(0)
	v_add_f32_e32 v96, v96, v97
	ds_bpermute_b32 v97, v116, v96
	v_mov_b32_e32 v200, v98
	v_mov_b32_e32 v201, v99
	v_cvt_pk_bf16_f32 v98, v108, v109
	v_cvt_pk_bf16_f32 v99, v110, v111
	v_mov_b32_e32 v202, v98
	v_mov_b32_e32 v203, v99
	v_bfe_u32 v206, v252, 4, 1
	v_mul_u32_u24_e32 v206, 24, v206
	v_mov_b32_e32 v207, 0
	v_lshl_add_u64 v[204:205], v[118:119], 0, v[206:207]
	v_permlane16_swap_b32_e32 v200, v202
	v_permlane16_swap_b32_e32 v201, v203
	global_store_dwordx4 v[204:205], v[200:203], off offset:256
	s_nop 1
	s_and_saveexec_b64 s[0:1], vcc
	s_cbranch_execz .LBB0_753
	s_waitcnt lgkmcnt(0)
	v_add_f32_e32 v96, v96, v97
	ds_write_b32 v114, v96 offset:64
.LBB0_753:
	s_or_b64 exec, exec, s[0:1]
	v_add3_u32 v96, s29, v161, 32
	s_waitcnt lgkmcnt(0)
	v_ashrrev_i32_e32 v97, 31, v96
	v_lshlrev_b32_e32 v98, 16, v150
	v_lshlrev_b64 v[96:97], 11, v[96:97]
	v_add_f32_e32 v92, v92, v98
	v_and_b32_e32 v98, 0xffff0000, v150
	v_lshl_add_u64 v[96:97], s[26:27], 0, v[96:97]
	v_add_f32_e32 v93, v93, v98
	v_lshlrev_b32_e32 v98, 16, v151
	v_lshl_add_u64 v[96:97], s[30:31], 1, v[96:97]
	v_add_f32_e32 v94, v94, v98
	v_and_b32_e32 v98, 0xffff0000, v151
	v_lshl_add_u64 v[96:97], v[96:97], 0, v[128:129]
	v_add_f32_e32 v95, v95, v98
	v_mul_f32_e32 v98, v93, v93
	v_lshl_add_u64 v[96:97], v[96:97], 0, v[112:113]
	v_fmac_f32_e32 v98, v92, v92
	v_cvt_pk_bf16_f32 v92, v92, v93
	v_cvt_pk_bf16_f32 v93, v94, v95
	v_mov_b32_e32 v200, v92
	v_mov_b32_e32 v201, v93
	v_lshlrev_b32_e32 v92, 16, v148
	v_add_f32_e32 v84, v84, v92
	v_and_b32_e32 v92, 0xffff0000, v148
	v_add_f32_e32 v85, v85, v92
	v_lshlrev_b32_e32 v92, 16, v149
	v_add_f32_e32 v86, v86, v92
	v_and_b32_e32 v92, 0xffff0000, v149
	v_add_f32_e32 v87, v87, v92
	v_mul_f32_e32 v92, v85, v85
	v_fmac_f32_e32 v92, v84, v84
	v_cvt_pk_bf16_f32 v84, v84, v85
	v_lshlrev_b32_e32 v85, 16, v146
	v_add_f32_e32 v88, v88, v85
	v_and_b32_e32 v85, 0xffff0000, v146
	v_add_f32_e32 v89, v89, v85
	v_lshlrev_b32_e32 v85, 16, v147
	v_mul_f32_e32 v93, v87, v87
	v_add_f32_e32 v90, v90, v85
	v_and_b32_e32 v85, 0xffff0000, v147
	v_mul_f32_e32 v99, v95, v95
	v_fmac_f32_e32 v93, v86, v86
	v_add_f32_e32 v91, v91, v85
	v_fmac_f32_e32 v99, v94, v94
	v_add_f32_e32 v92, v92, v93
	v_mul_f32_e32 v85, v89, v89
	v_mul_f32_e32 v93, v91, v91
	v_add_f32_e32 v98, v98, v99
	v_fmac_f32_e32 v85, v88, v88
	v_fmac_f32_e32 v93, v90, v90
	v_add_f32_e32 v92, v98, v92
	v_add_f32_e32 v85, v85, v93
	v_add_f32_e32 v85, v92, v85
	v_lshlrev_b32_e32 v92, 16, v142
	v_add_f32_e32 v92, v80, v92
	v_and_b32_e32 v80, 0xffff0000, v142
	v_add_f32_e32 v93, v81, v80
	v_lshlrev_b32_e32 v80, 16, v143
	v_add_f32_e32 v94, v82, v80
	v_and_b32_e32 v80, 0xffff0000, v143
	v_add_f32_e32 v95, v83, v80
	v_mul_f32_e32 v80, v93, v93
	v_mul_f32_e32 v81, v95, v95
	v_fmac_f32_e32 v80, v92, v92
	v_fmac_f32_e32 v81, v94, v94
	v_add_f32_e32 v80, v80, v81
	v_add_f32_e32 v80, v85, v80
	ds_bpermute_b32 v81, v115, v80
	v_cvt_pk_bf16_f32 v85, v86, v87
	v_mov_b32_e32 v202, v84
	v_mov_b32_e32 v203, v85
	v_bfe_u32 v206, v252, 4, 1
	v_mul_u32_u24_e32 v206, 24, v206
	v_mov_b32_e32 v207, 0
	v_lshl_add_u64 v[204:205], v[96:97], 0, v[206:207]
	v_permlane16_swap_b32_e32 v200, v202
	v_permlane16_swap_b32_e32 v201, v203
	global_store_dwordx4 v[204:205], v[200:203], off
	s_nop 1
	v_cvt_pk_bf16_f32 v82, v88, v89
	v_cvt_pk_bf16_f32 v83, v90, v91
	s_waitcnt lgkmcnt(0)
	v_add_f32_e32 v80, v80, v81
	ds_bpermute_b32 v81, v116, v80
	v_mov_b32_e32 v200, v82
	v_mov_b32_e32 v201, v83
	v_cvt_pk_bf16_f32 v82, v92, v93
	v_cvt_pk_bf16_f32 v83, v94, v95
	v_mov_b32_e32 v202, v82
	v_mov_b32_e32 v203, v83
	v_bfe_u32 v206, v252, 4, 1
	v_mul_u32_u24_e32 v206, 24, v206
	v_mov_b32_e32 v207, 0
	v_lshl_add_u64 v[204:205], v[96:97], 0, v[206:207]
	v_permlane16_swap_b32_e32 v200, v202
	v_permlane16_swap_b32_e32 v201, v203
	global_store_dwordx4 v[204:205], v[200:203], off offset:256
	s_nop 1
	s_and_saveexec_b64 s[0:1], vcc
	s_cbranch_execz .LBB0_755
	s_waitcnt lgkmcnt(0)
	v_add_f32_e32 v80, v80, v81
	ds_write_b32 v114, v80 offset:128
; __device__ __forceinline__ u32x2 pack4(float a, float b, float c, float d) { return u32x2{cvtpk(a, b), cvtpk(c, d)}; }
; __device__ __forceinline__ u32x2 pack4(const f32x4& v) { return u32x2{cvtpk(v[0], v[1]), cvtpk(v[2], v[3])}; }
; #define SBAR() __builtin_amdgcn_sched_barrier(0)
; __global__ void __launch_bounds__(512) fwd_megakernel(Params p) {
;     ...
;         for (int ai = 0; ai < 2; ++ai) { SBAR();
;           u32x2 hv[4][2][2];
;           #pragma unroll
;           for (int m = 0; m < 4; ++m) {
;             const bf16* hr = p_h1b + (long)(brow + ai * 128 + wr * 64 + m * 16 + fr) * DM + pn * 256 + wc * 32 + fq * 4;
;             #pragma unroll
;             for (int bj = 0; bj < 2; ++bj)
;               #pragma unroll
;               for (int n = 0; n < 2; ++n) hv[m][bj][n] = *reinterpret_cast<const u32x2*>(hr + bj * 128 + n * 16);
;           }
;           SBAR();
;           #pragma unroll
;           for (int m = 0; m < 4; ++m) {
;             int lrow = ai * 128 + wr * 64 + m * 16 + fr, row = brow + lrow; float ss = 0.f;
;             bf16* od = p_h2b + (long)row * DM + pn * 256 + wc * 32 + fq * 4;
;             #pragma unroll
;             for (int bj = 0; bj < 2; ++bj)
;               #pragma unroll
;               for (int n = 0; n < 2; ++n) {
;                 const u32x2 hw = hv[m][bj][n];
;                 f32x4 v = acc[ai][bj][m][n];
;                 v[0] += __uint_as_float(hw[0] << 16); v[1] += __uint_as_float(hw[0] & 0xffff0000u);
;                 v[2] += __uint_as_float(hw[1] << 16); v[3] += __uint_as_float(hw[1] & 0xffff0000u);
;                 ss += (v[0] * v[0] + v[1] * v[1]) + (v[2] * v[2] + v[3] * v[3]);
;                 *reinterpret_cast<u32x2*>(od + bj * 128 + n * 16) = pack4(v);
;               }
;             ss += __shfl_xor(ss, 16); ss += __shfl_xor(ss, 32);
;             if (fq == 0) red[wc * 256 + lrow] = ss;
;           }
.LBB0_755:
	s_or_b64 exec, exec, s[0:1]
	v_add3_u32 v80, s29, v161, 48
	s_waitcnt lgkmcnt(0)
	v_ashrrev_i32_e32 v81, 31, v80
	v_lshlrev_b32_e32 v82, 16, v140
	v_lshlrev_b64 v[80:81], 11, v[80:81]
	v_add_f32_e32 v76, v76, v82
	v_and_b32_e32 v82, 0xffff0000, v140
	v_lshl_add_u64 v[80:81], s[26:27], 0, v[80:81]
	v_add_f32_e32 v77, v77, v82
	v_lshlrev_b32_e32 v82, 16, v141
	v_lshl_add_u64 v[80:81], s[30:31], 1, v[80:81]
	v_add_f32_e32 v78, v78, v82
	v_and_b32_e32 v82, 0xffff0000, v141
	v_lshl_add_u64 v[80:81], v[80:81], 0, v[128:129]
	v_mov_b32_e32 v113, v129
	v_add_f32_e32 v79, v79, v82
	v_mul_f32_e32 v82, v77, v77
	v_lshl_add_u64 v[80:81], v[80:81], 0, v[112:113]
	v_fmac_f32_e32 v82, v76, v76
	v_cvt_pk_bf16_f32 v76, v76, v77
	v_cvt_pk_bf16_f32 v77, v78, v79
	v_mov_b32_e32 v200, v76
	v_mov_b32_e32 v201, v77
	v_lshlrev_b32_e32 v76, 16, v138
	v_add_f32_e32 v68, v68, v76
	v_and_b32_e32 v76, 0xffff0000, v138
	v_add_f32_e32 v69, v69, v76
	v_lshlrev_b32_e32 v76, 16, v139
	v_add_f32_e32 v70, v70, v76
	v_and_b32_e32 v76, 0xffff0000, v139
	v_add_f32_e32 v71, v71, v76
	v_mul_f32_e32 v76, v69, v69
	v_fmac_f32_e32 v76, v68, v68
	v_cvt_pk_bf16_f32 v68, v68, v69
	v_lshlrev_b32_e32 v69, 16, v136
	v_add_f32_e32 v72, v72, v69
	v_and_b32_e32 v69, 0xffff0000, v136
	v_add_f32_e32 v73, v73, v69
	v_lshlrev_b32_e32 v69, 16, v137
	v_mul_f32_e32 v77, v71, v71
	v_add_f32_e32 v74, v74, v69
	v_and_b32_e32 v69, 0xffff0000, v137
	v_mul_f32_e32 v83, v79, v79
	v_fmac_f32_e32 v77, v70, v70
	v_add_f32_e32 v75, v75, v69
	v_fmac_f32_e32 v83, v78, v78
	v_add_f32_e32 v76, v76, v77
	v_mul_f32_e32 v69, v73, v73
	v_mul_f32_e32 v77, v75, v75
	v_add_f32_e32 v82, v82, v83
	v_fmac_f32_e32 v69, v72, v72
	v_fmac_f32_e32 v77, v74, v74
	v_add_f32_e32 v76, v82, v76
	v_add_f32_e32 v69, v69, v77
	v_add_f32_e32 v69, v76, v69
	v_lshlrev_b32_e32 v76, 16, v134
	v_add_f32_e32 v76, v64, v76
	v_and_b32_e32 v64, 0xffff0000, v134
	v_add_f32_e32 v77, v65, v64
	v_lshlrev_b32_e32 v64, 16, v135
	v_add_f32_e32 v78, v66, v64
	v_and_b32_e32 v64, 0xffff0000, v135
	v_add_f32_e32 v79, v67, v64
	v_mul_f32_e32 v64, v77, v77
	v_mul_f32_e32 v65, v79, v79
	v_fmac_f32_e32 v64, v76, v76
	v_fmac_f32_e32 v65, v78, v78
	v_add_f32_e32 v64, v64, v65
	v_add_f32_e32 v64, v69, v64
	ds_bpermute_b32 v65, v115, v64
	v_cvt_pk_bf16_f32 v69, v70, v71
	v_mov_b32_e32 v202, v68
	v_mov_b32_e32 v203, v69
	v_bfe_u32 v206, v252, 4, 1
	v_mul_u32_u24_e32 v206, 24, v206
	v_mov_b32_e32 v207, 0
	v_lshl_add_u64 v[204:205], v[80:81], 0, v[206:207]
	v_permlane16_swap_b32_e32 v200, v202
	v_permlane16_swap_b32_e32 v201, v203
	global_store_dwordx4 v[204:205], v[200:203], off
	s_nop 1
	v_cvt_pk_bf16_f32 v66, v72, v73
	v_cvt_pk_bf16_f32 v67, v74, v75
	s_waitcnt lgkmcnt(0)
	v_add_f32_e32 v64, v64, v65
	ds_bpermute_b32 v65, v116, v64
	v_mov_b32_e32 v200, v66
	v_mov_b32_e32 v201, v67
	v_cvt_pk_bf16_f32 v66, v76, v77
	v_cvt_pk_bf16_f32 v67, v78, v79
	v_mov_b32_e32 v202, v66
	v_mov_b32_e32 v203, v67
	v_bfe_u32 v206, v252, 4, 1
	v_mul_u32_u24_e32 v206, 24, v206
	v_mov_b32_e32 v207, 0
	v_lshl_add_u64 v[204:205], v[80:81], 0, v[206:207]
	v_permlane16_swap_b32_e32 v200, v202
	v_permlane16_swap_b32_e32 v201, v203
	global_store_dwordx4 v[204:205], v[200:203], off offset:256
	s_nop 1
	s_and_saveexec_b64 s[0:1], vcc
	s_cbranch_execz .LBB0_757
	s_waitcnt lgkmcnt(0)
	v_add_f32_e32 v64, v64, v65
	ds_write_b32 v114, v64 offset:192
.LBB0_757:
	s_or_b64 exec, exec, s[0:1]
	v_add_u32_e32 v64, 0x80, v130
	s_waitcnt lgkmcnt(0)
	v_ashrrev_i32_e32 v65, 31, v64
	v_lshlrev_b64 v[94:95], 11, v[64:65]
	v_lshl_add_u64 v[64:65], v[132:133], 0, v[94:95]
	global_load_dwordx2 v[96:97], v[64:65], off
	global_load_dwordx2 v[98:99], v[64:65], off offset:32
	global_load_dwordx2 v[100:101], v[64:65], off offset:256
	global_load_dwordx2 v[102:103], v[64:65], off offset:288
	v_add_u32_e32 v64, 0x90, v130
	v_ashrrev_i32_e32 v65, 31, v64
	v_lshlrev_b64 v[92:93], 11, v[64:65]
	v_add_u32_e32 v82, 0xa0, v130
	v_lshl_add_u64 v[64:65], v[132:133], 0, v[92:93]
	v_ashrrev_i32_e32 v83, 31, v82
	global_load_dwordx2 v[90:91], v[64:65], off
	global_load_dwordx2 v[88:89], v[64:65], off offset:32
	global_load_dwordx2 v[86:87], v[64:65], off offset:256
	global_load_dwordx2 v[84:85], v[64:65], off offset:288
	v_lshlrev_b64 v[64:65], 11, v[82:83]
	v_add_u32_e32 v72, 0xb0, v130
	v_lshl_add_u64 v[64:65], v[132:133], 0, v[64:65]
	v_ashrrev_i32_e32 v73, 31, v72
	global_load_dwordx2 v[80:81], v[64:65], off
	global_load_dwordx2 v[78:79], v[64:65], off offset:32
	global_load_dwordx2 v[76:77], v[64:65], off offset:256
	global_load_dwordx2 v[74:75], v[64:65], off offset:288
	v_lshlrev_b64 v[64:65], 11, v[72:73]
	v_lshl_add_u64 v[64:65], v[132:133], 0, v[64:65]
	global_load_dwordx2 v[70:71], v[64:65], off
	global_load_dwordx2 v[68:69], v[64:65], off offset:32
	global_load_dwordx2 v[66:67], v[64:65], off offset:256
	s_nop 0
	global_load_dwordx2 v[64:65], v[64:65], off offset:288
	s_waitcnt vmcnt(15)
	v_lshlrev_b32_e32 v104, 16, v96
	v_and_b32_e32 v96, 0xffff0000, v96
	v_lshl_add_u64 v[94:95], s[26:27], 0, v[94:95]
	v_add_f32_e32 v61, v61, v96
	v_lshlrev_b32_e32 v96, 16, v97
	v_lshl_add_u64 v[94:95], s[30:31], 1, v[94:95]
	v_add_f32_e32 v62, v62, v96
	v_and_b32_e32 v96, 0xffff0000, v97
	v_lshl_add_u64 v[94:95], v[94:95], 0, v[128:129]
	v_add_f32_e32 v60, v60, v104
	v_add_f32_e32 v63, v63, v96
	v_mul_f32_e32 v96, v61, v61
	v_lshl_add_u64 v[94:95], v[94:95], 0, v[112:113]
	v_fmac_f32_e32 v96, v60, v60
	v_cvt_pk_bf16_f32 v60, v60, v61
	v_cvt_pk_bf16_f32 v61, v62, v63
	v_mov_b32_e32 v200, v60
	v_mov_b32_e32 v201, v61
	s_waitcnt vmcnt(14)
; __device__ __forceinline__ u32x2 pack4(float a, float b, float c, float d) { return u32x2{cvtpk(a, b), cvtpk(c, d)}; }
; __device__ __forceinline__ u32x2 pack4(const f32x4& v) { return u32x2{cvtpk(v[0], v[1]), cvtpk(v[2], v[3])}; }
; #define SBAR() __builtin_amdgcn_sched_barrier(0)
; __global__ void __launch_bounds__(512) fwd_megakernel(Params p) {
;     ...
;           SBAR();
;           #pragma unroll
;           for (int m = 0; m < 4; ++m) {
;             int lrow = ai * 128 + wr * 64 + m * 16 + fr, row = brow + lrow; float ss = 0.f;
;             bf16* od = p_h2b + (long)row * DM + pn * 256 + wc * 32 + fq * 4;
;             #pragma unroll
;             for (int bj = 0; bj < 2; ++bj)
;               #pragma unroll
;               for (int n = 0; n < 2; ++n) {
;                 const u32x2 hw = hv[m][bj][n];
;                 f32x4 v = acc[ai][bj][m][n];
;                 v[0] += __uint_as_float(hw[0] << 16); v[1] += __uint_as_float(hw[0] & 0xffff0000u);
;                 v[2] += __uint_as_float(hw[1] << 16); v[3] += __uint_as_float(hw[1] & 0xffff0000u);
;                 ss += (v[0] * v[0] + v[1] * v[1]) + (v[2] * v[2] + v[3] * v[3]);
;                 *reinterpret_cast<u32x2*>(od + bj * 128 + n * 16) = pack4(v);
;               }
;             ss += __shfl_xor(ss, 16); ss += __shfl_xor(ss, 32);
;             if (fq == 0) red[wc * 256 + lrow] = ss;
;           }
	v_lshlrev_b32_e32 v60, 16, v98
	v_add_f32_e32 v56, v56, v60
	v_and_b32_e32 v60, 0xffff0000, v98
	v_add_f32_e32 v57, v57, v60
	v_lshlrev_b32_e32 v60, 16, v99
	v_add_f32_e32 v58, v58, v60
	v_and_b32_e32 v60, 0xffff0000, v99
	v_add_f32_e32 v59, v59, v60
	v_mul_f32_e32 v60, v57, v57
	v_fmac_f32_e32 v60, v56, v56
	v_cvt_pk_bf16_f32 v56, v56, v57
	s_waitcnt vmcnt(13)
	v_lshlrev_b32_e32 v57, 16, v100
	v_add_f32_e32 v52, v52, v57
	v_and_b32_e32 v57, 0xffff0000, v100
	v_add_f32_e32 v53, v53, v57
	v_lshlrev_b32_e32 v57, 16, v101
	v_mul_f32_e32 v61, v59, v59
	v_add_f32_e32 v54, v54, v57
	v_and_b32_e32 v57, 0xffff0000, v101
	v_mul_f32_e32 v97, v63, v63
	v_fmac_f32_e32 v61, v58, v58
	v_add_f32_e32 v55, v55, v57
	v_fmac_f32_e32 v97, v62, v62
	v_add_f32_e32 v60, v60, v61
	v_mul_f32_e32 v57, v53, v53
	v_mul_f32_e32 v61, v55, v55
	v_add_f32_e32 v96, v96, v97
	v_fmac_f32_e32 v57, v52, v52
	v_fmac_f32_e32 v61, v54, v54
	v_add_f32_e32 v60, v96, v60
	v_add_f32_e32 v57, v57, v61
	v_add_f32_e32 v57, v60, v57
	s_waitcnt vmcnt(12)
	v_lshlrev_b32_e32 v60, 16, v102
	v_add_f32_e32 v60, v48, v60
	v_and_b32_e32 v48, 0xffff0000, v102
	v_add_f32_e32 v61, v49, v48
	v_lshlrev_b32_e32 v48, 16, v103
	v_add_f32_e32 v62, v50, v48
	v_and_b32_e32 v48, 0xffff0000, v103
	v_add_f32_e32 v63, v51, v48
	v_mul_f32_e32 v48, v61, v61
	v_mul_f32_e32 v49, v63, v63
	v_fmac_f32_e32 v48, v60, v60
	v_fmac_f32_e32 v49, v62, v62
	v_add_f32_e32 v48, v48, v49
	v_add_f32_e32 v48, v57, v48
	ds_bpermute_b32 v49, v115, v48
	v_cvt_pk_bf16_f32 v57, v58, v59
	v_mov_b32_e32 v202, v56
	v_mov_b32_e32 v203, v57
	v_bfe_u32 v206, v252, 4, 1
	v_mul_u32_u24_e32 v206, 24, v206
	v_mov_b32_e32 v207, 0
	v_lshl_add_u64 v[204:205], v[94:95], 0, v[206:207]
	v_permlane16_swap_b32_e32 v200, v202
	v_permlane16_swap_b32_e32 v201, v203
	global_store_dwordx4 v[204:205], v[200:203], off
	s_nop 1
	v_cvt_pk_bf16_f32 v50, v52, v53
	v_cvt_pk_bf16_f32 v51, v54, v55
	s_waitcnt lgkmcnt(0)
	v_add_f32_e32 v48, v48, v49
	ds_bpermute_b32 v49, v116, v48
	v_mov_b32_e32 v200, v50
	v_mov_b32_e32 v201, v51
	v_cvt_pk_bf16_f32 v50, v60, v61
	v_cvt_pk_bf16_f32 v51, v62, v63
	v_mov_b32_e32 v202, v50
	v_mov_b32_e32 v203, v51
	v_bfe_u32 v206, v252, 4, 1
	v_mul_u32_u24_e32 v206, 24, v206
	v_mov_b32_e32 v207, 0
	v_lshl_add_u64 v[204:205], v[94:95], 0, v[206:207]
	v_permlane16_swap_b32_e32 v200, v202
	v_permlane16_swap_b32_e32 v201, v203
	global_store_dwordx4 v[204:205], v[200:203], off offset:256
	s_nop 1
	s_and_saveexec_b64 s[0:1], vcc
	s_cbranch_execz .LBB0_759
	s_waitcnt lgkmcnt(0)
	v_add_f32_e32 v48, v48, v49
	ds_write_b32 v114, v48 offset:512
.LBB0_759:
	s_or_b64 exec, exec, s[0:1]
	s_waitcnt vmcnt(13)
	v_lshlrev_b32_e32 v50, 16, v90
	v_add_f32_e32 v44, v44, v50
	v_and_b32_e32 v50, 0xffff0000, v90
	s_waitcnt lgkmcnt(0)
	v_lshl_add_u64 v[48:49], s[26:27], 0, v[92:93]
	v_add_f32_e32 v45, v45, v50
	v_lshlrev_b32_e32 v50, 16, v91
	v_lshl_add_u64 v[48:49], s[30:31], 1, v[48:49]
	v_add_f32_e32 v46, v46, v50
	v_and_b32_e32 v50, 0xffff0000, v91
	v_lshl_add_u64 v[48:49], v[48:49], 0, v[128:129]
	v_mov_b32_e32 v113, v129
	v_add_f32_e32 v47, v47, v50
	v_mul_f32_e32 v50, v45, v45
	v_lshl_add_u64 v[48:49], v[48:49], 0, v[112:113]
	v_fmac_f32_e32 v50, v44, v44
	v_cvt_pk_bf16_f32 v44, v44, v45
	v_cvt_pk_bf16_f32 v45, v46, v47
	v_mov_b32_e32 v200, v44
	v_mov_b32_e32 v201, v45
	s_waitcnt vmcnt(12)
	v_lshlrev_b32_e32 v44, 16, v88
	v_add_f32_e32 v40, v40, v44
	v_and_b32_e32 v44, 0xffff0000, v88
	v_add_f32_e32 v41, v41, v44
	v_lshlrev_b32_e32 v44, 16, v89
	v_add_f32_e32 v42, v42, v44
	v_and_b32_e32 v44, 0xffff0000, v89
	v_add_f32_e32 v43, v43, v44
	v_mul_f32_e32 v44, v41, v41
	v_fmac_f32_e32 v44, v40, v40
	v_cvt_pk_bf16_f32 v40, v40, v41
	s_waitcnt vmcnt(11)
	v_lshlrev_b32_e32 v41, 16, v86
	v_add_f32_e32 v36, v36, v41
	v_and_b32_e32 v41, 0xffff0000, v86
	v_add_f32_e32 v37, v37, v41
	v_lshlrev_b32_e32 v41, 16, v87
	v_mul_f32_e32 v45, v43, v43
	v_add_f32_e32 v38, v38, v41
	v_and_b32_e32 v41, 0xffff0000, v87
	v_mul_f32_e32 v51, v47, v47
	v_fmac_f32_e32 v45, v42, v42
	v_add_f32_e32 v39, v39, v41
	v_fmac_f32_e32 v51, v46, v46
	v_add_f32_e32 v44, v44, v45
	v_mul_f32_e32 v41, v37, v37
	v_mul_f32_e32 v45, v39, v39
	v_add_f32_e32 v50, v50, v51
	v_fmac_f32_e32 v41, v36, v36
	v_fmac_f32_e32 v45, v38, v38
	v_add_f32_e32 v44, v50, v44
	v_add_f32_e32 v41, v41, v45
	v_add_f32_e32 v41, v44, v41
	s_waitcnt vmcnt(10)
	v_lshlrev_b32_e32 v44, 16, v84
	v_add_f32_e32 v44, v32, v44
	v_and_b32_e32 v32, 0xffff0000, v84
	v_add_f32_e32 v45, v33, v32
	v_lshlrev_b32_e32 v32, 16, v85
	v_add_f32_e32 v46, v34, v32
	v_and_b32_e32 v32, 0xffff0000, v85
	v_add_f32_e32 v47, v35, v32
	v_mul_f32_e32 v32, v45, v45
	v_mul_f32_e32 v33, v47, v47
	v_fmac_f32_e32 v32, v44, v44
	v_fmac_f32_e32 v33, v46, v46
	v_add_f32_e32 v32, v32, v33
	v_add_f32_e32 v32, v41, v32
	ds_bpermute_b32 v33, v115, v32
	v_cvt_pk_bf16_f32 v41, v42, v43
	v_mov_b32_e32 v202, v40
	v_mov_b32_e32 v203, v41
	v_bfe_u32 v206, v252, 4, 1
	v_mul_u32_u24_e32 v206, 24, v206
	v_mov_b32_e32 v207, 0
	v_lshl_add_u64 v[204:205], v[48:49], 0, v[206:207]
	v_permlane16_swap_b32_e32 v200, v202
	v_permlane16_swap_b32_e32 v201, v203
	global_store_dwordx4 v[204:205], v[200:203], off
	s_nop 1
	v_cvt_pk_bf16_f32 v34, v36, v37
	v_cvt_pk_bf16_f32 v35, v38, v39
	s_waitcnt lgkmcnt(0)
	v_add_f32_e32 v32, v32, v33
	ds_bpermute_b32 v33, v116, v32
	v_mov_b32_e32 v200, v34
	v_mov_b32_e32 v201, v35
	v_cvt_pk_bf16_f32 v34, v44, v45
	v_cvt_pk_bf16_f32 v35, v46, v47
	v_mov_b32_e32 v202, v34
	v_mov_b32_e32 v203, v35
	v_bfe_u32 v206, v252, 4, 1
	v_mul_u32_u24_e32 v206, 24, v206
	v_mov_b32_e32 v207, 0
	v_lshl_add_u64 v[204:205], v[48:49], 0, v[206:207]
	v_permlane16_swap_b32_e32 v200, v202
	v_permlane16_swap_b32_e32 v201, v203
	global_store_dwordx4 v[204:205], v[200:203], off offset:256
	s_nop 1
	s_and_saveexec_b64 s[0:1], vcc
	s_cbranch_execz .LBB0_761
	s_waitcnt lgkmcnt(0)
	v_add_f32_e32 v32, v32, v33
	ds_write_b32 v114, v32 offset:576
; __device__ __forceinline__ u32x2 pack4(float a, float b, float c, float d) { return u32x2{cvtpk(a, b), cvtpk(c, d)}; }
; __device__ __forceinline__ u32x2 pack4(const f32x4& v) { return u32x2{cvtpk(v[0], v[1]), cvtpk(v[2], v[3])}; }
; #define SBAR() __builtin_amdgcn_sched_barrier(0)
; __global__ void __launch_bounds__(512) fwd_megakernel(Params p) {
;     ...
;           SBAR();
;           #pragma unroll
;           for (int m = 0; m < 4; ++m) {
;             int lrow = ai * 128 + wr * 64 + m * 16 + fr, row = brow + lrow; float ss = 0.f;
;             bf16* od = p_h2b + (long)row * DM + pn * 256 + wc * 32 + fq * 4;
;             #pragma unroll
;             for (int bj = 0; bj < 2; ++bj)
;               #pragma unroll
;               for (int n = 0; n < 2; ++n) {
;                 const u32x2 hw = hv[m][bj][n];
;                 f32x4 v = acc[ai][bj][m][n];
;                 v[0] += __uint_as_float(hw[0] << 16); v[1] += __uint_as_float(hw[0] & 0xffff0000u);
;                 v[2] += __uint_as_float(hw[1] << 16); v[3] += __uint_as_float(hw[1] & 0xffff0000u);
;                 ss += (v[0] * v[0] + v[1] * v[1]) + (v[2] * v[2] + v[3] * v[3]);
;                 *reinterpret_cast<u32x2*>(od + bj * 128 + n * 16) = pack4(v);
;               }
;             ss += __shfl_xor(ss, 16); ss += __shfl_xor(ss, 32);
;             if (fq == 0) red[wc * 256 + lrow] = ss;
;           }
.LBB0_761:
	s_or_b64 exec, exec, s[0:1]
	s_waitcnt vmcnt(11)
	v_lshlrev_b32_e32 v34, 16, v80
	s_waitcnt lgkmcnt(0)
	v_lshlrev_b64 v[32:33], 11, v[82:83]
	v_add_f32_e32 v28, v28, v34
	v_and_b32_e32 v34, 0xffff0000, v80
	v_lshl_add_u64 v[32:33], s[26:27], 0, v[32:33]
	v_add_f32_e32 v29, v29, v34
	v_lshlrev_b32_e32 v34, 16, v81
	v_lshl_add_u64 v[32:33], s[30:31], 1, v[32:33]
	v_add_f32_e32 v30, v30, v34
	v_and_b32_e32 v34, 0xffff0000, v81
	v_lshl_add_u64 v[32:33], v[32:33], 0, v[128:129]
	v_add_f32_e32 v31, v31, v34
	v_mul_f32_e32 v34, v29, v29
	v_lshl_add_u64 v[32:33], v[32:33], 0, v[112:113]
	v_fmac_f32_e32 v34, v28, v28
	v_cvt_pk_bf16_f32 v28, v28, v29
	v_cvt_pk_bf16_f32 v29, v30, v31
	v_mov_b32_e32 v200, v28
	v_mov_b32_e32 v201, v29
	s_waitcnt vmcnt(10)
	v_lshlrev_b32_e32 v28, 16, v78
	v_add_f32_e32 v24, v24, v28
	v_and_b32_e32 v28, 0xffff0000, v78
	v_add_f32_e32 v25, v25, v28
	v_lshlrev_b32_e32 v28, 16, v79
	v_add_f32_e32 v26, v26, v28
	v_and_b32_e32 v28, 0xffff0000, v79
	v_add_f32_e32 v27, v27, v28
	v_mul_f32_e32 v28, v25, v25
	v_fmac_f32_e32 v28, v24, v24
	v_cvt_pk_bf16_f32 v24, v24, v25
	s_waitcnt vmcnt(9)
	v_lshlrev_b32_e32 v25, 16, v76
	v_add_f32_e32 v20, v20, v25
	v_and_b32_e32 v25, 0xffff0000, v76
	v_add_f32_e32 v21, v21, v25
	v_lshlrev_b32_e32 v25, 16, v77
	v_mul_f32_e32 v29, v27, v27
	v_add_f32_e32 v22, v22, v25
	v_and_b32_e32 v25, 0xffff0000, v77
	v_mul_f32_e32 v35, v31, v31
	v_fmac_f32_e32 v29, v26, v26
	v_add_f32_e32 v23, v23, v25
	v_fmac_f32_e32 v35, v30, v30
	v_add_f32_e32 v28, v28, v29
	v_mul_f32_e32 v25, v21, v21
	v_mul_f32_e32 v29, v23, v23
	v_add_f32_e32 v34, v34, v35
	v_fmac_f32_e32 v25, v20, v20
	v_fmac_f32_e32 v29, v22, v22
	v_add_f32_e32 v28, v34, v28
	v_add_f32_e32 v25, v25, v29
	v_add_f32_e32 v25, v28, v25
	s_waitcnt vmcnt(8)
	v_lshlrev_b32_e32 v28, 16, v74
	v_add_f32_e32 v28, v16, v28
	v_and_b32_e32 v16, 0xffff0000, v74
	v_add_f32_e32 v29, v17, v16
	v_lshlrev_b32_e32 v16, 16, v75
	v_add_f32_e32 v30, v18, v16
	v_and_b32_e32 v16, 0xffff0000, v75
	v_add_f32_e32 v31, v19, v16
	v_mul_f32_e32 v16, v29, v29
	v_mul_f32_e32 v17, v31, v31
	v_fmac_f32_e32 v16, v28, v28
	v_fmac_f32_e32 v17, v30, v30
	v_add_f32_e32 v16, v16, v17
	v_add_f32_e32 v16, v25, v16
	ds_bpermute_b32 v17, v115, v16
	v_cvt_pk_bf16_f32 v25, v26, v27
	v_mov_b32_e32 v202, v24
	v_mov_b32_e32 v203, v25
	v_bfe_u32 v206, v252, 4, 1
	v_mul_u32_u24_e32 v206, 24, v206
	v_mov_b32_e32 v207, 0
	v_lshl_add_u64 v[204:205], v[32:33], 0, v[206:207]
	v_permlane16_swap_b32_e32 v200, v202
	v_permlane16_swap_b32_e32 v201, v203
	global_store_dwordx4 v[204:205], v[200:203], off
	s_nop 1
	v_cvt_pk_bf16_f32 v18, v20, v21
	v_cvt_pk_bf16_f32 v19, v22, v23
	s_waitcnt lgkmcnt(0)
	v_add_f32_e32 v16, v16, v17
	ds_bpermute_b32 v17, v116, v16
	v_mov_b32_e32 v200, v18
	v_mov_b32_e32 v201, v19
	v_cvt_pk_bf16_f32 v18, v28, v29
	v_cvt_pk_bf16_f32 v19, v30, v31
	v_mov_b32_e32 v202, v18
	v_mov_b32_e32 v203, v19
	v_bfe_u32 v206, v252, 4, 1
	v_mul_u32_u24_e32 v206, 24, v206
	v_mov_b32_e32 v207, 0
	v_lshl_add_u64 v[204:205], v[32:33], 0, v[206:207]
	v_permlane16_swap_b32_e32 v200, v202
	v_permlane16_swap_b32_e32 v201, v203
	global_store_dwordx4 v[204:205], v[200:203], off offset:256
	s_nop 1
	s_and_saveexec_b64 s[0:1], vcc
	s_cbranch_execz .LBB0_763
	s_waitcnt lgkmcnt(0)
	v_add_f32_e32 v16, v16, v17
	ds_write_b32 v114, v16 offset:640
.LBB0_763:
	s_or_b64 exec, exec, s[0:1]
	s_waitcnt vmcnt(9)
	v_lshlrev_b32_e32 v18, 16, v70
	s_waitcnt lgkmcnt(0)
	v_lshlrev_b64 v[16:17], 11, v[72:73]
	v_add_f32_e32 v12, v12, v18
	v_and_b32_e32 v18, 0xffff0000, v70
	v_lshl_add_u64 v[16:17], s[26:27], 0, v[16:17]
	v_add_f32_e32 v13, v13, v18
	v_lshlrev_b32_e32 v18, 16, v71
	v_lshl_add_u64 v[16:17], s[30:31], 1, v[16:17]
	v_add_f32_e32 v14, v14, v18
	v_and_b32_e32 v18, 0xffff0000, v71
	v_lshl_add_u64 v[16:17], v[16:17], 0, v[128:129]
	v_mov_b32_e32 v113, v129
	v_add_f32_e32 v15, v15, v18
	v_mul_f32_e32 v18, v13, v13
	v_lshl_add_u64 v[16:17], v[16:17], 0, v[112:113]
	v_fmac_f32_e32 v18, v12, v12
	v_cvt_pk_bf16_f32 v12, v12, v13
	v_cvt_pk_bf16_f32 v13, v14, v15
	v_mov_b32_e32 v200, v12
	v_mov_b32_e32 v201, v13
	s_waitcnt vmcnt(8)
	v_lshlrev_b32_e32 v12, 16, v68
	v_add_f32_e32 v8, v8, v12
	v_and_b32_e32 v12, 0xffff0000, v68
	v_add_f32_e32 v9, v9, v12
	v_lshlrev_b32_e32 v12, 16, v69
	v_add_f32_e32 v10, v10, v12
	v_and_b32_e32 v12, 0xffff0000, v69
	v_add_f32_e32 v11, v11, v12
	v_mul_f32_e32 v12, v9, v9
	v_fmac_f32_e32 v12, v8, v8
	v_cvt_pk_bf16_f32 v8, v8, v9
	s_waitcnt vmcnt(7)
	v_lshlrev_b32_e32 v9, 16, v66
	v_add_f32_e32 v4, v4, v9
	v_and_b32_e32 v9, 0xffff0000, v66
	v_add_f32_e32 v5, v5, v9
	v_lshlrev_b32_e32 v9, 16, v67
	v_mul_f32_e32 v13, v11, v11
	v_add_f32_e32 v6, v6, v9
	v_and_b32_e32 v9, 0xffff0000, v67
	v_mul_f32_e32 v19, v15, v15
	v_fmac_f32_e32 v13, v10, v10
	v_add_f32_e32 v7, v7, v9
	v_fmac_f32_e32 v19, v14, v14
	v_add_f32_e32 v12, v12, v13
	v_mul_f32_e32 v9, v5, v5
	v_mul_f32_e32 v13, v7, v7
	v_add_f32_e32 v18, v18, v19
	v_fmac_f32_e32 v9, v4, v4
	v_fmac_f32_e32 v13, v6, v6
	v_add_f32_e32 v12, v18, v12
	v_add_f32_e32 v9, v9, v13
	v_add_f32_e32 v9, v12, v9
	s_waitcnt vmcnt(6)
	v_lshlrev_b32_e32 v12, 16, v64
	v_add_f32_e32 v12, v0, v12
	v_and_b32_e32 v0, 0xffff0000, v64
	v_add_f32_e32 v13, v1, v0
	v_lshlrev_b32_e32 v0, 16, v65
	v_add_f32_e32 v14, v2, v0
	v_and_b32_e32 v0, 0xffff0000, v65
	v_add_f32_e32 v15, v3, v0
	v_mul_f32_e32 v0, v13, v13
	v_mul_f32_e32 v1, v15, v15
	v_fmac_f32_e32 v0, v12, v12
	v_fmac_f32_e32 v1, v14, v14
	v_add_f32_e32 v0, v0, v1
	v_add_f32_e32 v0, v9, v0
	ds_bpermute_b32 v1, v115, v0
	v_cvt_pk_bf16_f32 v9, v10, v11
	v_mov_b32_e32 v202, v8
	v_mov_b32_e32 v203, v9
	v_bfe_u32 v206, v252, 4, 1
	v_mul_u32_u24_e32 v206, 24, v206
	v_mov_b32_e32 v207, 0
	v_lshl_add_u64 v[204:205], v[16:17], 0, v[206:207]
	v_permlane16_swap_b32_e32 v200, v202
	v_permlane16_swap_b32_e32 v201, v203
	global_store_dwordx4 v[204:205], v[200:203], off
	s_nop 1
	v_cvt_pk_bf16_f32 v2, v4, v5
	v_cvt_pk_bf16_f32 v3, v6, v7
	s_waitcnt lgkmcnt(0)
	v_add_f32_e32 v0, v0, v1
	ds_bpermute_b32 v1, v116, v0
	v_mov_b32_e32 v200, v2
	v_mov_b32_e32 v201, v3
	v_cvt_pk_bf16_f32 v2, v12, v13
	v_cvt_pk_bf16_f32 v3, v14, v15
	v_mov_b32_e32 v202, v2
	v_mov_b32_e32 v203, v3
	v_bfe_u32 v206, v252, 4, 1
	v_mul_u32_u24_e32 v206, 24, v206
	v_mov_b32_e32 v207, 0
	v_lshl_add_u64 v[204:205], v[16:17], 0, v[206:207]
	v_permlane16_swap_b32_e32 v200, v202
	v_permlane16_swap_b32_e32 v201, v203
	global_store_dwordx4 v[204:205], v[200:203], off offset:256
	s_nop 1
	s_and_saveexec_b64 s[0:1], vcc
	s_cbranch_execz .LBB0_765
	s_waitcnt lgkmcnt(0)
	v_add_f32_e32 v0, v0, v1
	ds_write_b32 v114, v0 offset:704
